# v21 + S5 constant fragments: 16 loads issued together before the conversions; MoE tile lookup: gcnt[13..23] fetched with gcnt[0..12] in one round trip instead of 11 dependent loads per tile
# speedup vs baseline: 1.0193x; 1.0062x over previous
.LBB0_149:
	v_readlane_b32 s0, v237, 31
	s_lshl_b32 s0, s0, 2
	v_mov_b32_e32 v0, v128
	s_and_b32 s56, s0, 28
	v_mov_b32_e32 v1, v128
	v_lshl_add_u32 v0, s56, 6, v0
	v_and_b32_e32 v39, 0xffffffc0, v0
	v_and_b32_e32 v2, 15, v1
	v_lshrrev_b32_e32 v0, 1, v1
	v_readlane_b32 s1, v237, 32
	v_and_b32_e32 v38, 63, v1
	v_and_b32_e32 v1, 24, v0
	v_or_b32_e32 v28, v2, v39
	v_writelane_b32 v237, s0, 36
	v_cmp_gt_u32_e64 s[0:1], 32, v38
	v_mov_b32_e32 v0, 0
	v_ashrrev_i32_e32 v29, 31, v28
	v_lshlrev_b32_e32 v32, 2, v1
	v_or_b32_e32 v22, 16, v28
	v_mov_b32_e32 v4, 0
	v_mov_b32_e32 v5, 0
	v_mov_b32_e32 v6, 0
	v_mov_b32_e32 v7, 0
	v_mov_b32_e32 v8, 0
	v_mov_b32_e32 v9, 0
	v_mov_b32_e32 v10, 0
	v_mov_b32_e32 v11, 0
	s_and_saveexec_b64 s[6:7], s[0:1]
	s_cbranch_execz .LBB0_151
	s_add_u32 s4, s88, 0x3d0a000
	s_addc_u32 s5, s89, 0
	v_lshlrev_b64 v[2:3], 7, v[28:29]
	v_lshl_add_u64 v[2:3], s[4:5], 0, v[2:3]
	v_mov_b32_e32 v33, v0
	v_lshl_add_u64 v[2:3], v[2:3], 0, v[32:33]
	v_ashrrev_i32_e32 v23, 31, v22
	global_load_dwordx4 v[180:183], v[2:3], off offset:16
	global_load_dwordx4 v[184:187], v[2:3], off
	v_lshlrev_b64 v[2:3], 7, v[22:23]
	v_lshl_add_u64 v[2:3], s[4:5], 0, v[2:3]
	v_lshl_add_u64 v[2:3], v[2:3], 0, v[32:33]
	global_load_dwordx4 v[188:191], v[2:3], off
	global_load_dwordx4 v[192:195], v[2:3], off offset:16
.LBB0_151:
	s_or_b64 exec, exec, s[6:7]
	v_or_b32_e32 v36, 32, v28
	v_or_b32_e32 v34, 48, v28
	v_mov_b32_e32 v1, 0
	v_mov_b32_e32 v2, 0
	v_mov_b32_e32 v3, 0
	v_mov_b32_e32 v12, 0
	v_mov_b32_e32 v13, 0
	v_mov_b32_e32 v14, 0
	v_mov_b32_e32 v15, 0
	s_and_saveexec_b64 s[6:7], s[0:1]
	s_cbranch_execz .LBB0_153
	s_add_u32 s4, s88, 0x3d0a000
	v_ashrrev_i32_e32 v37, 31, v36
	v_ashrrev_i32_e32 v35, 31, v34
	s_addc_u32 s5, s89, 0
	v_lshlrev_b64 v[0:1], 7, v[36:37]
	v_lshlrev_b64 v[16:17], 7, v[34:35]
	v_lshl_add_u64 v[0:1], s[4:5], 0, v[0:1]
	v_mov_b32_e32 v33, 0
	v_lshl_add_u64 v[16:17], s[4:5], 0, v[16:17]
	v_lshl_add_u64 v[0:1], v[0:1], 0, v[32:33]
	v_lshl_add_u64 v[20:21], v[16:17], 0, v[32:33]
	global_load_dwordx4 v[196:199], v[0:1], off offset:16
	s_nop 0
	global_load_dwordx4 v[200:203], v[0:1], off
	s_nop 0
	global_load_dwordx4 v[204:207], v[20:21], off
	global_load_dwordx4 v[208:211], v[20:21], off offset:16
.LBB0_153:
	s_or_b64 exec, exec, s[6:7]
	v_mov_b32_e32 v20, 0
	v_mov_b32_e32 v16, 0
	v_mov_b32_e32 v17, 0
	v_mov_b32_e32 v18, 0
	v_mov_b32_e32 v19, 0
	v_mov_b32_e32 v24, 0
	v_mov_b32_e32 v25, 0
	v_mov_b32_e32 v26, 0
	v_mov_b32_e32 v27, 0
	s_and_saveexec_b64 s[6:7], s[0:1]
	s_cbranch_execz .LBB0_155
	v_lshlrev_b64 v[16:17], 7, v[28:29]
	v_lshl_add_u64 v[16:17], s[88:89], 0, v[16:17]
	v_mov_b32_e32 v33, 0
	v_ashrrev_i32_e32 v23, 31, v22
	v_lshl_add_u64 v[16:17], v[16:17], 0, v[32:33]
	s_mov_b64 s[4:5], 0x3d0a040
	v_lshlrev_b64 v[22:23], 7, v[22:23]
	v_lshl_add_u64 v[24:25], v[16:17], 0, s[4:5]
	v_add_co_u32_e32 v16, vcc, 0x3d0a000, v16
	v_lshl_add_u64 v[22:23], s[88:89], 0, v[22:23]
	s_mov_b32 s12, 0x3d0a000
	v_addc_co_u32_e32 v17, vcc, 0, v17, vcc
	v_lshl_add_u64 v[22:23], v[22:23], 0, v[32:33]
	v_add_co_u32_e32 v28, vcc, s12, v22
	global_load_dwordx4 v[212:215], v[16:17], off offset:64
	s_nop 0
	global_load_dwordx4 v[216:219], v[24:25], off offset:16
	v_addc_co_u32_e32 v29, vcc, 0, v23, vcc
	v_lshl_add_u64 v[22:23], v[22:23], 0, s[4:5]
	global_load_dwordx4 v[220:223], v[28:29], off offset:64
	global_load_dwordx4 v[224:227], v[22:23], off offset:16
.LBB0_155:
	s_or_b64 exec, exec, s[6:7]
	v_mov_b32_e32 v21, 0
	v_mov_b32_e32 v22, 0
	v_mov_b32_e32 v23, 0
	v_mov_b32_e32 v28, 0
	v_mov_b32_e32 v29, 0
	v_mov_b32_e32 v30, 0
	v_mov_b32_e32 v31, 0
	s_and_saveexec_b64 s[6:7], s[0:1]
	s_cbranch_execz .LBB0_157
	v_ashrrev_i32_e32 v37, 31, v36
	v_lshlrev_b64 v[20:21], 7, v[36:37]
	v_lshl_add_u64 v[20:21], s[88:89], 0, v[20:21]
	v_mov_b32_e32 v33, 0
	v_ashrrev_i32_e32 v35, 31, v34
	v_lshl_add_u64 v[20:21], v[20:21], 0, v[32:33]
	s_mov_b64 s[0:1], 0x3d0a040
	v_lshlrev_b64 v[34:35], 7, v[34:35]
	v_lshl_add_u64 v[28:29], v[20:21], 0, s[0:1]
	v_add_co_u32_e32 v20, vcc, 0x3d0a000, v20
	v_lshl_add_u64 v[34:35], s[88:89], 0, v[34:35]
	s_mov_b32 s4, 0x3d0a000
	v_addc_co_u32_e32 v21, vcc, 0, v21, vcc
	v_lshl_add_u64 v[36:37], v[34:35], 0, v[32:33]
	v_add_co_u32_e32 v32, vcc, s4, v36
	global_load_dwordx4 v[228:231], v[20:21], off offset:64
	s_nop 0
	global_load_dwordx4 v[232:235], v[28:29], off offset:16
	v_addc_co_u32_e32 v33, vcc, 0, v37, vcc
	v_lshl_add_u64 v[36:37], v[36:37], 0, s[0:1]
	global_load_dwordx4 v[238:241], v[32:33], off offset:64
	global_load_dwordx4 v[242:245], v[36:37], off offset:16
	s_waitcnt vmcnt(15)
	v_cvt_pk_bf16_f32 v6, v180, v181
	s_waitcnt vmcnt(14)
	v_cvt_pk_bf16_f32 v4, v184, v185
	v_cvt_pk_bf16_f32 v5, v186, v187
	v_cvt_pk_bf16_f32 v7, v182, v183
	s_waitcnt vmcnt(13)
	v_cvt_pk_bf16_f32 v8, v188, v189
	v_cvt_pk_bf16_f32 v9, v190, v191
	s_waitcnt vmcnt(12)
	v_cvt_pk_bf16_f32 v10, v192, v193
	v_cvt_pk_bf16_f32 v11, v194, v195
	s_waitcnt vmcnt(10)
	v_cvt_pk_bf16_f32 v0, v200, v201
	v_cvt_pk_bf16_f32 v1, v202, v203
	v_cvt_pk_bf16_f32 v2, v196, v197
	v_cvt_pk_bf16_f32 v3, v198, v199
	s_waitcnt vmcnt(9)
	v_cvt_pk_bf16_f32 v12, v204, v205
	v_cvt_pk_bf16_f32 v13, v206, v207
	s_waitcnt vmcnt(8)
	v_cvt_pk_bf16_f32 v14, v208, v209
	v_cvt_pk_bf16_f32 v15, v210, v211
	s_waitcnt vmcnt(7)
	v_cvt_pk_bf16_f32 v16, v212, v213
	v_cvt_pk_bf16_f32 v17, v214, v215
	s_waitcnt vmcnt(6)
	v_cvt_pk_bf16_f32 v18, v216, v217
	v_cvt_pk_bf16_f32 v19, v218, v219
	s_waitcnt vmcnt(5)
	v_cvt_pk_bf16_f32 v24, v220, v221
	v_cvt_pk_bf16_f32 v25, v222, v223
	s_waitcnt vmcnt(4)
	v_cvt_pk_bf16_f32 v26, v224, v225
	v_cvt_pk_bf16_f32 v27, v226, v227
	s_waitcnt vmcnt(3)
	v_cvt_pk_bf16_f32 v20, v228, v229
	v_cvt_pk_bf16_f32 v21, v230, v231
	s_waitcnt vmcnt(2)
	v_cvt_pk_bf16_f32 v22, v232, v233
	v_cvt_pk_bf16_f32 v23, v234, v235
	s_waitcnt vmcnt(1)
	v_cvt_pk_bf16_f32 v28, v238, v239
	v_cvt_pk_bf16_f32 v29, v240, v241
	s_waitcnt vmcnt(0)
	v_cvt_pk_bf16_f32 v30, v242, v243
	v_cvt_pk_bf16_f32 v31, v244, v245

.LBB0_308:
	v_mov_b32_e32 v0, v128
	v_mov_b32_e32 v4, 0
	v_ashrrev_i32_e32 v0, 6, v0
	v_add_u32_e32 v32, s56, v0
	v_mov_b32_e32 v0, v128
	v_lshlrev_b32_e32 v42, 6, v32
	v_and_b32_e32 v41, 63, v0
	v_and_b32_e32 v40, 15, v0
	v_lshrrev_b32_e32 v0, 1, v0
	v_and_b32_e32 v1, 24, v0
	v_or_b32_e32 v28, v42, v40
	v_cmp_gt_u32_e64 s[0:1], 32, v41
	v_mov_b32_e32 v0, 0
	v_ashrrev_i32_e32 v29, 31, v28
	v_lshlrev_b32_e32 v34, 2, v1
	v_or_b32_e32 v26, 16, v28
	v_mov_b32_e32 v5, 0
	v_mov_b32_e32 v6, 0
	v_mov_b32_e32 v7, 0
	v_mov_b32_e32 v8, 0
	v_mov_b32_e32 v9, 0
	v_mov_b32_e32 v10, 0
	v_mov_b32_e32 v11, 0
	s_and_saveexec_b64 s[2:3], s[0:1]
	s_cbranch_execz .LBB0_310
	s_add_u32 s4, s88, 0x3d0a000
	s_addc_u32 s5, s89, 0
	v_lshlrev_b64 v[2:3], 7, v[28:29]
	v_lshl_add_u64 v[2:3], s[4:5], 0, v[2:3]
	v_mov_b32_e32 v35, v0
	v_lshl_add_u64 v[6:7], v[2:3], 0, v[34:35]
	v_ashrrev_i32_e32 v27, 31, v26
	global_load_dwordx4 v[180:183], v[6:7], off offset:16
	global_load_dwordx4 v[184:187], v[6:7], off
	v_lshlrev_b64 v[6:7], 7, v[26:27]
	v_lshl_add_u64 v[6:7], s[4:5], 0, v[6:7]
	v_lshl_add_u64 v[6:7], v[6:7], 0, v[34:35]
	global_load_dwordx4 v[188:191], v[6:7], off
	global_load_dwordx4 v[192:195], v[6:7], off offset:16
.LBB0_310:
	s_or_b64 exec, exec, s[2:3]
	v_or_b32_e32 v38, 32, v28
	v_or_b32_e32 v36, 48, v28
	v_mov_b32_e32 v1, 0
	v_mov_b32_e32 v2, 0
	v_mov_b32_e32 v3, 0
	v_mov_b32_e32 v12, 0
	v_mov_b32_e32 v13, 0
	v_mov_b32_e32 v14, 0
	v_mov_b32_e32 v15, 0
	s_and_saveexec_b64 s[2:3], s[0:1]
	s_cbranch_execz .LBB0_312
	s_add_u32 s4, s88, 0x3d0a000
	v_ashrrev_i32_e32 v39, 31, v38
	v_ashrrev_i32_e32 v37, 31, v36
	s_addc_u32 s5, s89, 0
	v_lshlrev_b64 v[0:1], 7, v[38:39]
	v_lshlrev_b64 v[16:17], 7, v[36:37]
	v_lshl_add_u64 v[0:1], s[4:5], 0, v[0:1]
	v_mov_b32_e32 v35, 0
	v_lshl_add_u64 v[16:17], s[4:5], 0, v[16:17]
	v_lshl_add_u64 v[12:13], v[0:1], 0, v[34:35]
	v_lshl_add_u64 v[20:21], v[16:17], 0, v[34:35]
	global_load_dwordx4 v[196:199], v[12:13], off offset:16
	s_nop 0
	global_load_dwordx4 v[200:203], v[12:13], off
	s_nop 0
	global_load_dwordx4 v[204:207], v[20:21], off
	s_nop 0
	global_load_dwordx4 v[208:211], v[20:21], off offset:16
.LBB0_312:
	s_or_b64 exec, exec, s[2:3]
	v_mov_b32_e32 v24, 0
	v_mov_b32_e32 v16, 0
	v_mov_b32_e32 v17, 0
	v_mov_b32_e32 v18, 0
	v_mov_b32_e32 v19, 0
	v_mov_b32_e32 v20, 0
	v_mov_b32_e32 v21, 0
	v_mov_b32_e32 v22, 0
	v_mov_b32_e32 v23, 0
	s_and_saveexec_b64 s[2:3], s[0:1]
	s_cbranch_execz .LBB0_314
	v_lshlrev_b64 v[16:17], 7, v[28:29]
	v_lshl_add_u64 v[16:17], s[88:89], 0, v[16:17]
	v_mov_b32_e32 v35, 0
	v_lshl_add_u64 v[16:17], v[16:17], 0, v[34:35]
	s_mov_b64 s[4:5], 0x3d0a040
	v_lshl_add_u64 v[20:21], v[16:17], 0, s[4:5]
	v_add_co_u32_e32 v16, vcc, 0x3d0a000, v16
	v_ashrrev_i32_e32 v27, 31, v26
	s_nop 0
	v_addc_co_u32_e32 v17, vcc, 0, v17, vcc
	global_load_dwordx4 v[212:215], v[16:17], off offset:64
	s_nop 0
	global_load_dwordx4 v[216:219], v[20:21], off offset:16
	v_lshlrev_b64 v[20:21], 7, v[26:27]
	v_lshl_add_u64 v[20:21], s[88:89], 0, v[20:21]
	s_mov_b32 s6, 0x3d0a000
	v_lshl_add_u64 v[20:21], v[20:21], 0, v[34:35]
	v_add_co_u32_e32 v22, vcc, s6, v20
	s_nop 1
	v_addc_co_u32_e32 v23, vcc, 0, v21, vcc
	v_lshl_add_u64 v[20:21], v[20:21], 0, s[4:5]
	global_load_dwordx4 v[220:223], v[22:23], off offset:64
	global_load_dwordx4 v[224:227], v[20:21], off offset:16
.LBB0_314:
	s_or_b64 exec, exec, s[2:3]
	v_mov_b32_e32 v25, 0
	v_mov_b32_e32 v26, 0
	v_mov_b32_e32 v27, 0
	v_mov_b32_e32 v28, 0
	v_mov_b32_e32 v29, 0
	v_mov_b32_e32 v30, 0
	v_mov_b32_e32 v31, 0
	s_and_saveexec_b64 s[2:3], s[0:1]
	s_cbranch_execz .LBB0_316
	v_ashrrev_i32_e32 v39, 31, v38
	v_lshlrev_b64 v[24:25], 7, v[38:39]
	v_lshl_add_u64 v[24:25], s[88:89], 0, v[24:25]
	v_mov_b32_e32 v35, 0
	v_lshl_add_u64 v[24:25], v[24:25], 0, v[34:35]
	s_mov_b64 s[0:1], 0x3d0a040
	v_lshl_add_u64 v[28:29], v[24:25], 0, s[0:1]
	v_add_co_u32_e32 v24, vcc, 0x3d0a000, v24
	v_ashrrev_i32_e32 v37, 31, v36
	s_nop 0
	v_addc_co_u32_e32 v25, vcc, 0, v25, vcc
	global_load_dwordx4 v[228:231], v[24:25], off offset:64
	s_nop 0
	global_load_dwordx4 v[232:235], v[28:29], off offset:16
	v_lshlrev_b64 v[28:29], 7, v[36:37]
	v_lshl_add_u64 v[28:29], s[88:89], 0, v[28:29]
	s_mov_b32 s4, 0x3d0a000
	v_lshl_add_u64 v[28:29], v[28:29], 0, v[34:35]
	v_add_co_u32_e32 v30, vcc, s4, v28
	s_nop 1
	v_addc_co_u32_e32 v31, vcc, 0, v29, vcc
	v_lshl_add_u64 v[28:29], v[28:29], 0, s[0:1]
	global_load_dwordx4 v[238:241], v[30:31], off offset:64
	global_load_dwordx4 v[242:245], v[28:29], off offset:16
	s_waitcnt vmcnt(14)
	v_cvt_pk_bf16_f32 v8, v184, v185
	v_cvt_pk_bf16_f32 v9, v186, v187
	v_cvt_pk_bf16_f32 v10, v180, v181
	v_cvt_pk_bf16_f32 v11, v182, v183
	s_waitcnt vmcnt(13)
	v_cvt_pk_bf16_f32 v4, v188, v189
	v_cvt_pk_bf16_f32 v5, v190, v191
	s_waitcnt vmcnt(12)
	v_cvt_pk_bf16_f32 v6, v192, v193
	v_cvt_pk_bf16_f32 v7, v194, v195
	s_waitcnt vmcnt(10)
	v_cvt_pk_bf16_f32 v12, v200, v201
	v_cvt_pk_bf16_f32 v13, v202, v203
	v_cvt_pk_bf16_f32 v14, v196, v197
	v_cvt_pk_bf16_f32 v15, v198, v199
	s_waitcnt vmcnt(9)
	v_cvt_pk_bf16_f32 v0, v204, v205
	v_cvt_pk_bf16_f32 v1, v206, v207
	s_waitcnt vmcnt(8)
	v_cvt_pk_bf16_f32 v2, v208, v209
	v_cvt_pk_bf16_f32 v3, v210, v211
	s_waitcnt vmcnt(7)
	v_cvt_pk_bf16_f32 v20, v212, v213
	v_cvt_pk_bf16_f32 v21, v214, v215
	s_waitcnt vmcnt(6)
	v_cvt_pk_bf16_f32 v22, v216, v217
	v_cvt_pk_bf16_f32 v23, v218, v219
	s_waitcnt vmcnt(5)
	v_cvt_pk_bf16_f32 v16, v220, v221
	v_cvt_pk_bf16_f32 v17, v222, v223
	s_waitcnt vmcnt(4)
	v_cvt_pk_bf16_f32 v18, v224, v225
	v_cvt_pk_bf16_f32 v19, v226, v227
	s_waitcnt vmcnt(3)
	v_cvt_pk_bf16_f32 v28, v228, v229
	v_cvt_pk_bf16_f32 v29, v230, v231
	s_waitcnt vmcnt(2)
	v_cvt_pk_bf16_f32 v30, v232, v233
	v_cvt_pk_bf16_f32 v31, v234, v235
	s_waitcnt vmcnt(1)
	v_cvt_pk_bf16_f32 v24, v238, v239
	v_cvt_pk_bf16_f32 v25, v240, v241
	s_waitcnt vmcnt(0)
	v_cvt_pk_bf16_f32 v26, v242, v243
	v_cvt_pk_bf16_f32 v27, v244, v245

.LBB0_646:
	s_or_b64 exec, exec, s[0:1]
	s_waitcnt lgkmcnt(0)
	v_mov_b32_e32 v0, 0x3d00000
	s_barrier
	global_load_dwordx4 v[2:5], v0, s[88:89]
	global_load_dwordx4 v[6:9], v0, s[88:89] offset:64
	s_add_u32 s92, s88, 0x3d00000
	v_mov_b32_e32 v0, 0
	s_addc_u32 s93, s89, 0
	global_load_dwordx4 v[10:13], v0, s[92:93] offset:16
	global_load_dwordx4 v[14:17], v0, s[92:93] offset:32
	global_load_dwordx4 v[18:21], v0, s[92:93] offset:48
	s_mov_b64 s[0:1], s[88:89]
	s_mov_b64 s[2:3], s[90:91]
	s_add_u32 s88, s0, 0x8500000
	s_addc_u32 s89, s1, 0
	s_add_u32 s90, s0, 0x3d00034
	s_addc_u32 s91, s1, 0
	s_add_u32 s94, s0, 0x3d00038
	s_addc_u32 s95, s1, 0
	s_add_u32 s2, s0, 0x3d0003c
	s_addc_u32 s3, s1, 0
	s_add_u32 s96, s0, 0x3d00040
	s_addc_u32 s97, s1, 0
	global_load_dwordx4 v[22:25], v0, s[96:97] offset:16
	v_writelane_b32 v236, s2, 8
	s_waitcnt vmcnt(5)
	v_add_u32_e32 v1, 0x7f, v2
	v_add_u32_e32 v2, 0x7f, v3
	v_add_u32_e32 v3, 0x7f, v4
	v_ashrrev_i32_e32 v1, 7, v1
	v_ashrrev_i32_e32 v2, 7, v2
	v_add_u32_e32 v4, 0x7f, v5
	v_ashrrev_i32_e32 v3, 7, v3
	v_add_u32_e32 v1, v2, v1
	s_waitcnt vmcnt(4)
	v_add_u32_e32 v5, 0x7f, v6
	v_add_u32_e32 v6, 0x7f, v7
	v_add_u32_e32 v7, 0x7f, v8
	v_add_u32_e32 v8, 0x7f, v9
	v_ashrrev_i32_e32 v4, 7, v4
	s_waitcnt vmcnt(3)
	v_add_u32_e32 v9, 0x7f, v10
	v_add_u32_e32 v1, v1, v3
	v_add_u32_e32 v10, 0x7f, v11
	v_ashrrev_i32_e32 v2, 7, v9
	v_add_u32_e32 v1, v1, v4
	v_writelane_b32 v236, s3, 9
	s_add_u32 s2, s0, 0x3d00044
	v_add_u32_e32 v11, 0x7f, v12
	v_ashrrev_i32_e32 v9, 7, v10
	v_add_u32_e32 v1, v1, v2
	s_addc_u32 s3, s1, 0
	v_add_u32_e32 v12, 0x7f, v13
	v_ashrrev_i32_e32 v10, 7, v11
	v_add_u32_e32 v1, v1, v9
	v_writelane_b32 v236, s2, 6
	s_waitcnt vmcnt(2)
	v_add_u32_e32 v13, 0x7f, v14
	v_ashrrev_i32_e32 v11, 7, v12
	v_add_u32_e32 v1, v1, v10
	v_writelane_b32 v236, s3, 7
	s_add_u32 s2, s0, 0x3d00048
	v_add_u32_e32 v14, 0x7f, v15
	v_ashrrev_i32_e32 v12, 7, v13
	v_add_u32_e32 v1, v1, v11
	s_addc_u32 s3, s1, 0
	v_add_u32_e32 v15, 0x7f, v16
	v_ashrrev_i32_e32 v13, 7, v14
	v_add_u32_e32 v1, v1, v12
	v_writelane_b32 v236, s2, 2
	v_add_u32_e32 v16, 0x7f, v17
	v_ashrrev_i32_e32 v14, 7, v15
	v_add_u32_e32 v1, v1, v13
	v_writelane_b32 v236, s3, 3
	s_add_u32 s2, s0, 0x3d0004c
	s_waitcnt vmcnt(1)
	v_add_u32_e32 v17, 0x7f, v18
	v_ashrrev_i32_e32 v15, 7, v16
	v_add_u32_e32 v1, v1, v14
	s_addc_u32 s3, s1, 0
	v_add_u32_e32 v18, 0x7f, v19
	v_ashrrev_i32_e32 v17, 7, v17
	v_add_u32_e32 v1, v1, v15
	v_writelane_b32 v236, s2, 4
	v_add_u32_e32 v19, 0x7f, v20
	v_ashrrev_i32_e32 v16, 7, v18
	v_add_u32_e32 v1, v1, v17
	v_writelane_b32 v236, s3, 5
	s_add_u32 s2, s0, 0x3d00050
	v_add_u32_e32 v20, 0x7f, v21
	v_ashrrev_i32_e32 v19, 7, v19
	v_add_u32_e32 v1, v1, v16
	s_addc_u32 s3, s1, 0
	v_ashrrev_i32_e32 v18, 7, v20
	v_add_u32_e32 v1, v1, v19
	v_writelane_b32 v237, s2, 62
	v_ashrrev_i32_e32 v5, 7, v5
	v_add_u32_e32 v1, v1, v18
	v_writelane_b32 v237, s3, 63
	s_add_u32 s2, s0, 0x3d00054
	v_ashrrev_i32_e32 v6, 7, v6
	v_add_u32_e32 v1, v1, v5
	s_addc_u32 s3, s1, 0
	v_ashrrev_i32_e32 v7, 7, v7
	v_add_u32_e32 v1, v1, v6
	v_writelane_b32 v236, s2, 0
	v_ashrrev_i32_e32 v8, 7, v8
	s_waitcnt vmcnt(0)
	v_add_u32_e32 v2, 0x7f, v22
	v_add_u32_e32 v1, v1, v7
	v_writelane_b32 v236, s3, 1
	s_add_u32 s2, s0, 0x3d00058
	v_add_u32_e32 v3, 0x7f, v23
	v_ashrrev_i32_e32 v2, 7, v2
	v_add_u32_e32 v1, v1, v8
	s_addc_u32 s3, s1, 0
	v_add_u32_e32 v4, 0x7f, v24
	v_ashrrev_i32_e32 v3, 7, v3
	v_add_u32_e32 v1, v1, v2
	s_add_u32 s0, s0, 0x3d0005c
	v_add_u32_e32 v9, 0x7f, v25
	v_add_u32_e32 v1, v1, v3
	v_ashrrev_i32_e32 v3, 7, v4
	v_writelane_b32 v237, s2, 60
	s_addc_u32 s1, s1, 0
	v_ashrrev_i32_e32 v2, 7, v9
	v_add_u32_e32 v1, v1, v3
	v_writelane_b32 v237, s3, 61
	v_writelane_b32 v236, s0, 10
	v_add_u32_e32 v1, v1, v2
	v_lshlrev_b32_e32 v129, 3, v1
	v_writelane_b32 v236, s1, 11
	v_readlane_b32 s0, v237, 31
	v_readlane_b32 s84, v237, 23
	v_readlane_b32 s86, v237, 21
	v_cmp_ge_i32_e32 vcc, s0, v129
	v_mov_b32_e32 v12, v128
	s_and_b64 vcc, exec, vcc
	v_readlane_b32 s85, v237, 24
	v_readlane_b32 s87, v237, 22
	v_readlane_b32 s1, v237, 32
	s_cbranch_vccnz .LBB0_734
	global_load_dword v238, v0, s[92:93] offset:52
	global_load_dword v239, v0, s[92:93] offset:56
	global_load_dword v240, v0, s[92:93] offset:60
	global_load_dword v241, v0, s[92:93] offset:64
	global_load_dword v242, v0, s[92:93] offset:68
	global_load_dword v243, v0, s[92:93] offset:72
	global_load_dword v244, v0, s[92:93] offset:76
	global_load_dword v245, v0, s[92:93] offset:80
	global_load_dword v246, v0, s[92:93] offset:84
	global_load_dword v247, v0, s[92:93] offset:88
	global_load_dword v248, v0, s[92:93] offset:92
	global_load_dword v13, v0, s[92:93] offset:48
	global_load_dwordx4 v[4:7], v0, s[92:93] offset:16
	global_load_dwordx4 v[8:11], v0, s[92:93]
	s_nop 0
	global_load_dwordx4 v[0:3], v0, s[92:93] offset:32
	v_readlane_b32 s0, v237, 31
	s_ashr_i32 s2, s0, 3
	v_readlane_b32 s1, v237, 32
	s_cmp_gt_i32 s2, -1
	s_cselect_b64 s[0:1], -1, 0
	s_lshl_b32 s3, s2, 7
	s_waitcnt vmcnt(3)
	v_add_u32_e32 v36, 0x7f, v13
	s_waitcnt vmcnt(2)
	v_add_u32_e32 v21, 0x7f, v4
	s_waitcnt vmcnt(1)
	v_add_u32_e32 v14, 0x7f, v8
	v_add_u32_e32 v15, 0x7f, v9
	v_ashrrev_i32_e32 v14, 7, v14
	v_ashrrev_i32_e32 v15, 7, v15
	v_add_u32_e32 v16, 0x7f, v10
	v_add_u32_e32 v15, v15, v14
	v_ashrrev_i32_e32 v16, 7, v16
	v_add_u32_e32 v19, 0x7f, v11
	v_add_u32_e32 v18, v16, v15
	v_ashrrev_i32_e32 v19, 7, v19
	v_add_u32_e32 v20, v19, v18
	v_ashrrev_i32_e32 v21, 7, v21
	v_add_u32_e32 v23, 0x7f, v5
	v_add_u32_e32 v22, v21, v20
	v_ashrrev_i32_e32 v23, 7, v23
	v_add_u32_e32 v25, 0x7f, v6
	v_add_u32_e32 v24, v23, v22
	v_ashrrev_i32_e32 v25, 7, v25
	v_add_u32_e32 v27, 0x7f, v7
	v_add_u32_e32 v26, v25, v24
	v_ashrrev_i32_e32 v27, 7, v27
	s_waitcnt vmcnt(0)
	v_add_u32_e32 v28, 0x7f, v0
	v_add_u32_e32 v29, v27, v26
	v_ashrrev_i32_e32 v28, 7, v28
	v_add_u32_e32 v17, v9, v8
	v_add_u32_e32 v31, v28, v29
	v_add_u32_e32 v28, 0x7f, v1
	v_add_u32_e32 v16, v10, v17
	v_ashrrev_i32_e32 v28, 7, v28
	v_add_u32_e32 v19, v11, v16
	v_add_u32_e32 v33, v28, v31
	v_add_u32_e32 v28, 0x7f, v2
	v_add_u32_e32 v21, v4, v19
	v_ashrrev_i32_e32 v28, 7, v28
	v_add_u32_e32 v23, v5, v21
	v_add_u32_e32 v35, v28, v33
	v_add_u32_e32 v28, 0x7f, v3
	v_add_u32_e32 v25, v6, v23
	v_ashrrev_i32_e32 v28, 7, v28
	v_cmp_lt_i32_e32 vcc, s2, v14
	v_add_u32_e32 v27, v7, v25
	v_add_u32_e32 v37, v28, v35
	v_ashrrev_i32_e32 v36, 7, v36
	s_and_b64 s[0:1], s[0:1], vcc
	v_add_u32_e32 v30, v0, v27
	v_add_u32_e32 v36, v36, v37
	s_and_b64 s[4:5], s[0:1], exec
	v_add_u32_e32 v32, v1, v30
	v_cmp_ge_i32_e32 vcc, s2, v37
	v_cmp_lt_i32_e64 s[56:57], s2, v36
	s_cselect_b32 s3, s3, 0
	v_add_u32_e32 v34, v2, v32
	s_and_b64 s[4:5], vcc, s[56:57]
	v_cmp_ge_i32_e64 s[8:9], s2, v14
	v_cmp_lt_i32_e64 s[10:11], s2, v15
	v_cmp_ge_i32_e64 s[12:13], s2, v15
	v_cmp_lt_i32_e64 s[14:15], s2, v18
	v_cmp_ge_i32_e64 s[18:19], s2, v18
	v_cmp_lt_i32_e64 s[20:21], s2, v20
	v_cmp_ge_i32_e64 s[22:23], s2, v20
	v_cmp_lt_i32_e64 s[24:25], s2, v22
	v_cmp_ge_i32_e64 s[26:27], s2, v22
	v_cmp_lt_i32_e64 s[28:29], s2, v24
	v_cmp_ge_i32_e64 s[30:31], s2, v24
	v_cmp_lt_i32_e64 s[34:35], s2, v26
	v_cmp_ge_i32_e64 s[36:37], s2, v26
	v_cmp_lt_i32_e64 s[38:39], s2, v29
	v_cmp_ge_i32_e64 s[40:41], s2, v29
	v_cmp_lt_i32_e64 s[42:43], s2, v31
	v_cmp_ge_i32_e64 s[44:45], s2, v31
	v_cmp_lt_i32_e64 s[46:47], s2, v33
	v_cmp_ge_i32_e64 s[48:49], s2, v33
	v_cmp_lt_i32_e64 s[50:51], s2, v35
	v_cmp_ge_i32_e64 s[52:53], s2, v35
	v_cmp_lt_i32_e64 s[54:55], s2, v37
	v_add_u32_e32 v28, v3, v34
	s_andn2_b64 vcc, exec, s[4:5]
	s_cbranch_vccnz .LBB0_649
	v_sub_u32_e32 v0, s2, v37
	v_lshlrev_b32_e32 v139, 7, v0
	v_mov_b32_e32 v130, 12
	v_mov_b32_e32 v142, v13
	v_mov_b32_e32 v143, v28
	s_branch .LBB0_650

.LBB0_650:
	v_mov_b32_e32 v0, 0
	v_mov_b32_e32 v3, v238
	v_cmp_ge_i32_e32 vcc, s2, v36
	v_add_u32_e32 v4, v13, v28
	v_add_u32_e32 v1, 0x7f, v3
	v_ashrrev_i32_e32 v1, 7, v1
	v_add_u32_e32 v2, v1, v36
	v_cmp_lt_i32_e64 s[0:1], s2, v2
	s_and_b64 s[0:1], vcc, s[0:1]
	s_andn2_b64 vcc, exec, s[0:1]
	s_cbranch_vccnz .LBB0_652
	v_sub_u32_e32 v1, s2, v36
	v_lshlrev_b32_e32 v139, 7, v1
	v_mov_b32_e32 v130, 13
	v_mov_b32_e32 v142, v3
	v_mov_b32_e32 v143, v4
.LBB0_652:
	v_mov_b32_e32 v1, v239
	v_cmp_ge_i32_e32 vcc, s2, v2
	v_add_u32_e32 v5, v3, v4
	v_add_u32_e32 v0, 0x7f, v1
	v_ashrrev_i32_e32 v0, 7, v0
	v_add_u32_e32 v0, v0, v2
	v_cmp_lt_i32_e64 s[0:1], s2, v0
	s_and_b64 s[0:1], vcc, s[0:1]
	s_andn2_b64 vcc, exec, s[0:1]
	s_cbranch_vccnz .LBB0_654
	v_sub_u32_e32 v2, s2, v2
	v_lshlrev_b32_e32 v139, 7, v2
	v_mov_b32_e32 v130, 14
	v_mov_b32_e32 v142, v1
	v_mov_b32_e32 v143, v5
.LBB0_654:
	v_readlane_b32 s0, v236, 8
	v_mov_b32_e32 v2, 0
	v_readlane_b32 s1, v236, 9
	v_cmp_ge_i32_e32 vcc, s2, v0
	v_add_u32_e32 v1, v1, v5
	s_nop 2
	v_mov_b32_e32 v4, v240
	v_add_u32_e32 v3, 0x7f, v4
	v_ashrrev_i32_e32 v3, 7, v3
	v_add_u32_e32 v3, v3, v0
	v_cmp_lt_i32_e64 s[0:1], s2, v3
	s_and_b64 s[0:1], vcc, s[0:1]
	s_andn2_b64 vcc, exec, s[0:1]
	s_cbranch_vccnz .LBB0_656
	v_sub_u32_e32 v0, s2, v0
	v_lshlrev_b32_e32 v139, 7, v0
	v_mov_b32_e32 v130, 15
	v_mov_b32_e32 v142, v4
	v_mov_b32_e32 v143, v1
.LBB0_656:
	v_mov_b32_e32 v2, v241
	v_cmp_ge_i32_e32 vcc, s2, v3
	v_add_u32_e32 v5, v4, v1
	v_add_u32_e32 v0, 0x7f, v2
	v_ashrrev_i32_e32 v0, 7, v0
	v_add_u32_e32 v0, v0, v3
	v_cmp_lt_i32_e64 s[0:1], s2, v0
	s_and_b64 s[0:1], vcc, s[0:1]
	s_andn2_b64 vcc, exec, s[0:1]
	s_cbranch_vccnz .LBB0_658
	v_sub_u32_e32 v1, s2, v3
	v_lshlrev_b32_e32 v139, 7, v1
	v_mov_b32_e32 v130, 16
	v_mov_b32_e32 v142, v2
	v_mov_b32_e32 v143, v5
.LBB0_658:
	v_readlane_b32 s0, v236, 6
	v_mov_b32_e32 v4, 0
	v_readlane_b32 s1, v236, 7
	v_cmp_ge_i32_e32 vcc, s2, v0
	v_add_u32_e32 v5, v2, v5
	s_nop 2
	v_mov_b32_e32 v3, v242
	v_add_u32_e32 v1, 0x7f, v3
	v_ashrrev_i32_e32 v1, 7, v1
	v_add_u32_e32 v1, v1, v0
	v_cmp_lt_i32_e64 s[0:1], s2, v1
	s_and_b64 s[0:1], vcc, s[0:1]
	s_andn2_b64 vcc, exec, s[0:1]
	s_cbranch_vccnz .LBB0_660
	v_sub_u32_e32 v0, s2, v0
	v_lshlrev_b32_e32 v139, 7, v0
	v_mov_b32_e32 v130, 17
	v_mov_b32_e32 v142, v3
	v_mov_b32_e32 v143, v5
.LBB0_660:
	v_readlane_b32 s0, v236, 2
	v_readlane_b32 s1, v236, 3
	v_cmp_ge_i32_e32 vcc, s2, v1
	v_add_u32_e32 v5, v3, v5
	s_nop 2
	v_mov_b32_e32 v2, v243
	v_add_u32_e32 v0, 0x7f, v2
	v_ashrrev_i32_e32 v0, 7, v0
	v_add_u32_e32 v0, v0, v1
	v_cmp_lt_i32_e64 s[0:1], s2, v0
	s_and_b64 s[0:1], vcc, s[0:1]
	s_andn2_b64 vcc, exec, s[0:1]
	s_cbranch_vccnz .LBB0_662
	v_sub_u32_e32 v1, s2, v1
	v_lshlrev_b32_e32 v139, 7, v1
	v_mov_b32_e32 v130, 18
	v_mov_b32_e32 v142, v2
	v_mov_b32_e32 v143, v5
.LBB0_662:
	v_readlane_b32 s0, v236, 4
	v_mov_b32_e32 v3, 0
	v_readlane_b32 s1, v236, 5
	v_cmp_ge_i32_e32 vcc, s2, v0
	v_add_u32_e32 v2, v2, v5
	s_nop 2
	v_mov_b32_e32 v4, v244
	v_add_u32_e32 v1, 0x7f, v4
	v_ashrrev_i32_e32 v1, 7, v1
	v_add_u32_e32 v1, v1, v0
	v_cmp_lt_i32_e64 s[0:1], s2, v1
	s_and_b64 s[0:1], vcc, s[0:1]
	s_andn2_b64 vcc, exec, s[0:1]
	s_cbranch_vccnz .LBB0_664
	v_sub_u32_e32 v0, s2, v0
	v_lshlrev_b32_e32 v139, 7, v0
	v_mov_b32_e32 v130, 19
	v_mov_b32_e32 v142, v4
	v_mov_b32_e32 v143, v2
.LBB0_664:
	v_readlane_b32 s0, v237, 62
	v_readlane_b32 s1, v237, 63
	v_cmp_ge_i32_e32 vcc, s2, v1
	v_add_u32_e32 v5, v4, v2
	s_nop 2
	v_mov_b32_e32 v3, v245
	v_add_u32_e32 v0, 0x7f, v3
	v_ashrrev_i32_e32 v0, 7, v0
	v_add_u32_e32 v0, v0, v1
	v_cmp_lt_i32_e64 s[0:1], s2, v0
	s_and_b64 s[0:1], vcc, s[0:1]
	s_andn2_b64 vcc, exec, s[0:1]
	s_cbranch_vccnz .LBB0_666
	v_sub_u32_e32 v1, s2, v1
	v_lshlrev_b32_e32 v139, 7, v1
	v_mov_b32_e32 v130, 20
	v_mov_b32_e32 v142, v3
	v_mov_b32_e32 v143, v5
.LBB0_666:
	v_readlane_b32 s0, v236, 0
	v_mov_b32_e32 v1, 0
	v_readlane_b32 s1, v236, 1
	v_cmp_ge_i32_e32 vcc, s2, v0
	v_add_u32_e32 v3, v3, v5
	s_nop 2
	v_mov_b32_e32 v4, v246
	v_add_u32_e32 v2, 0x7f, v4
	v_ashrrev_i32_e32 v2, 7, v2
	v_add_u32_e32 v2, v2, v0
	v_cmp_lt_i32_e64 s[0:1], s2, v2
	s_and_b64 s[0:1], vcc, s[0:1]
	s_andn2_b64 vcc, exec, s[0:1]
	s_cbranch_vccnz .LBB0_668
	v_sub_u32_e32 v0, s2, v0
	v_lshlrev_b32_e32 v139, 7, v0
	v_mov_b32_e32 v130, 21
	v_mov_b32_e32 v142, v4
	v_mov_b32_e32 v143, v3
.LBB0_668:
	v_readlane_b32 s0, v237, 60
	v_readlane_b32 s1, v237, 61
	v_cmp_ge_i32_e32 vcc, s2, v2
	v_add_u32_e32 v3, v4, v3
	s_nop 2
	v_mov_b32_e32 v0, v247
	v_add_u32_e32 v1, 0x7f, v0
	v_ashrrev_i32_e32 v1, 7, v1
	v_add_u32_e32 v1, v1, v2
	v_cmp_lt_i32_e64 s[0:1], s2, v1
	s_and_b64 s[0:1], vcc, s[0:1]
	s_andn2_b64 vcc, exec, s[0:1]
	s_cbranch_vccnz .LBB0_670
	v_sub_u32_e32 v2, s2, v2
	v_lshlrev_b32_e32 v139, 7, v2
	v_mov_b32_e32 v130, 22
	v_mov_b32_e32 v142, v0
	v_mov_b32_e32 v143, v3
.LBB0_670:
	v_readlane_b32 s0, v236, 10
	v_mov_b32_e32 v131, 0
	v_readlane_b32 s1, v236, 11
	v_cmp_ge_i32_e32 vcc, s2, v1
	s_mov_b64 s[74:75], s[96:97]
	s_nop 2
	v_mov_b32_e32 v2, v248
	v_add_u32_e32 v4, 0x7f, v2
	v_ashrrev_i32_e32 v4, 7, v4
	v_add_u32_e32 v4, v4, v1
	v_cmp_lt_i32_e64 s[0:1], s2, v4
	s_and_b64 s[0:1], vcc, s[0:1]
	s_andn2_b64 vcc, exec, s[0:1]
	s_cbranch_vccnz .LBB0_672
	v_add_u32_e32 v143, v0, v3
	v_sub_u32_e32 v0, s2, v1
	v_lshlrev_b32_e32 v139, 7, v0
	v_mov_b32_e32 v130, 23
	v_mov_b32_e32 v142, v2

.LBB0_674:
	global_load_dword v238, v131, s[92:93] offset:52
	global_load_dword v239, v131, s[92:93] offset:56
	global_load_dword v240, v131, s[92:93] offset:60
	global_load_dword v241, v131, s[92:93] offset:64
	global_load_dword v242, v131, s[92:93] offset:68
	global_load_dword v243, v131, s[92:93] offset:72
	global_load_dword v244, v131, s[92:93] offset:76
	global_load_dword v245, v131, s[92:93] offset:80
	global_load_dword v246, v131, s[92:93] offset:84
	global_load_dword v247, v131, s[92:93] offset:88
	global_load_dword v248, v131, s[92:93] offset:92
	global_load_dwordx4 v[72:75], v131, s[92:93]
	global_load_dwordx4 v[68:71], v131, s[92:93] offset:16
	global_load_dwordx4 v[64:67], v131, s[92:93] offset:32
	global_load_dword v76, v131, s[92:93] offset:48
	v_readlane_b32 s8, v237, 56
	v_readlane_b32 s10, v237, 58
	v_readlane_b32 s11, v237, 59
	s_add_i32 s17, s82, s10
	v_cmp_lt_i32_e64 s[10:11], s17, v129
	s_and_b64 s[0:1], s[10:11], exec
	s_cselect_b32 s83, s17, s82
	s_ashr_i32 s2, s83, 3
	s_cmp_gt_i32 s2, -1
	s_cselect_b64 s[0:1], -1, 0
	s_lshl_b32 s4, s2, 7
	v_readlane_b32 s9, v237, 57
	v_cmp_ge_i32_e64 s[8:9], s17, v129
	s_waitcnt vmcnt(3)
	v_add_u32_e32 v77, 0x7f, v72
	v_add_u32_e32 v79, 0x7f, v73
	v_add_u32_e32 v80, 0x7f, v74
	v_ashrrev_i32_e32 v96, 7, v77
	v_ashrrev_i32_e32 v77, 7, v79
	v_add_u32_e32 v81, 0x7f, v75
	v_ashrrev_i32_e32 v79, 7, v80
	v_add_u32_e32 v99, v77, v96
	s_waitcnt vmcnt(2)
	v_add_u32_e32 v82, 0x7f, v68
	v_ashrrev_i32_e32 v80, 7, v81
	v_add_u32_e32 v98, v79, v99
	v_add_u32_e32 v83, 0x7f, v69
	v_ashrrev_i32_e32 v81, 7, v82
	v_add_u32_e32 v97, v80, v98
	v_add_u32_e32 v84, 0x7f, v70
	v_ashrrev_i32_e32 v82, 7, v83
	v_add_u32_e32 v95, v81, v97
	v_add_u32_e32 v78, v73, v72
	v_add_u32_e32 v85, 0x7f, v71
	v_ashrrev_i32_e32 v84, 7, v84
	v_add_u32_e32 v94, v82, v95
	s_waitcnt vmcnt(1)
	v_add_u32_e32 v86, 0x7f, v64
	s_waitcnt vmcnt(0)
	v_add_u32_e32 v91, 0x7f, v76
	v_add_u32_e32 v88, v74, v78
	v_ashrrev_i32_e32 v92, 7, v85
	v_add_u32_e32 v93, v84, v94
	v_add_u32_e32 v87, 0x7f, v65
	v_add_u32_e32 v89, 0x7f, v66
	v_add_u32_e32 v90, 0x7f, v67
	v_ashrrev_i32_e32 v86, 7, v86
	v_ashrrev_i32_e32 v103, 7, v91
	v_add_u32_e32 v91, v75, v88
	v_add_u32_e32 v92, v92, v93
	v_ashrrev_i32_e32 v100, 7, v87
	v_ashrrev_i32_e32 v101, 7, v89
	v_ashrrev_i32_e32 v102, 7, v90
	v_add_u32_e32 v90, v68, v91
	v_add_u32_e32 v89, v86, v92
	v_add_u32_e32 v87, v69, v90
	v_add_u32_e32 v86, v100, v89
	v_add_u32_e32 v85, v70, v87
	v_add_u32_e32 v84, v101, v86
	v_cmp_lt_i32_e32 vcc, s2, v96
	v_add_u32_e32 v83, v71, v85
	v_add_u32_e32 v100, v102, v84
	s_and_b64 s[58:59], s[0:1], vcc
	v_add_u32_e32 v82, v64, v83
	v_add_u32_e32 v77, v103, v100
	s_and_b64 s[0:1], s[58:59], exec
	v_add_u32_e32 v81, v65, v82
	v_cmp_ge_i32_e32 vcc, s2, v100
	v_cmp_lt_i32_e64 s[60:61], s2, v77
	s_cselect_b32 s4, s4, 0
	v_add_u32_e32 v79, v66, v81
	s_and_b64 s[60:61], vcc, s[60:61]
	v_cmp_ge_i32_e64 s[52:53], s2, v96
	v_cmp_lt_i32_e64 s[56:57], s2, v99
	v_cmp_ge_i32_e64 s[48:49], s2, v99
	v_cmp_lt_i32_e64 s[54:55], s2, v98
	v_cmp_ge_i32_e64 s[44:45], s2, v98
	v_cmp_lt_i32_e64 s[50:51], s2, v97
	v_cmp_ge_i32_e64 s[42:43], s2, v97
	v_cmp_lt_i32_e64 s[46:47], s2, v95
	v_cmp_ge_i32_e64 s[38:39], s2, v95
	v_cmp_lt_i32_e64 s[40:41], s2, v94
	v_cmp_ge_i32_e64 s[34:35], s2, v94
	v_cmp_lt_i32_e64 s[36:37], s2, v93
	v_cmp_ge_i32_e64 s[28:29], s2, v93
	v_cmp_lt_i32_e64 s[30:31], s2, v92
	v_cmp_ge_i32_e64 s[24:25], s2, v92
	v_cmp_lt_i32_e64 s[26:27], s2, v89
	v_cmp_ge_i32_e64 s[20:21], s2, v89
	v_cmp_lt_i32_e64 s[22:23], s2, v86
	v_cmp_ge_i32_e64 s[14:15], s2, v86
	v_cmp_lt_i32_e64 s[18:19], s2, v84
	v_cmp_ge_i32_e64 s[0:1], s2, v84
	v_cmp_lt_i32_e64 s[12:13], s2, v100
	s_andn2_b64 vcc, exec, s[60:61]
	v_add_u32_e32 v80, v67, v79
	s_cbranch_vccnz .LBB0_676
	v_sub_u32_e32 v64, s2, v100
	v_lshlrev_b32_e32 v150, 7, v64
	v_mov_b32_e32 v134, 12
	v_mov_b32_e32 v151, v76
	v_mov_b32_e32 v152, v80
	s_branch .LBB0_677

.LBB0_677:
	v_mov_b32_e32 v66, v238
	v_cmp_ge_i32_e32 vcc, s2, v77
	v_readlane_b32 s12, v237, 25
	v_add_u32_e32 v64, v76, v80
	v_readlane_b32 s13, v237, 26
	v_add_u32_e32 v65, 0x7f, v66
	v_ashrrev_i32_e32 v65, 7, v65
	v_add_u32_e32 v65, v65, v77
	v_cmp_lt_i32_e64 s[0:1], s2, v65
	s_and_b64 s[0:1], vcc, s[0:1]
	s_andn2_b64 vcc, exec, s[0:1]
	s_cbranch_vccnz .LBB0_679
	v_sub_u32_e32 v67, s2, v77
	v_lshlrev_b32_e32 v150, 7, v67
	v_mov_b32_e32 v134, 13
	v_mov_b32_e32 v151, v66
	v_mov_b32_e32 v152, v64
.LBB0_679:
	v_mov_b32_e32 v67, v239
	v_add_u32_e32 v66, v66, v64
	v_cmp_ge_i32_e32 vcc, s2, v65
	v_add_u32_e32 v64, 0x7f, v67
	v_ashrrev_i32_e32 v64, 7, v64
	v_add_u32_e32 v64, v64, v65
	v_cmp_lt_i32_e64 s[0:1], s2, v64
	s_and_b64 s[0:1], vcc, s[0:1]
	s_andn2_b64 vcc, exec, s[0:1]
	s_cbranch_vccnz .LBB0_681
	v_sub_u32_e32 v65, s2, v65
	v_lshlrev_b32_e32 v150, 7, v65
	v_mov_b32_e32 v134, 14
	v_mov_b32_e32 v151, v67
	v_mov_b32_e32 v152, v66
.LBB0_681:
	v_readlane_b32 s0, v236, 8
	v_readlane_b32 s1, v236, 9
	v_add_u32_e32 v66, v67, v66
	v_cmp_ge_i32_e32 vcc, s2, v64
	s_nop 2
	v_mov_b32_e32 v67, v240
	v_add_u32_e32 v65, 0x7f, v67
	v_ashrrev_i32_e32 v65, 7, v65
	v_add_u32_e32 v65, v65, v64
	v_cmp_lt_i32_e64 s[0:1], s2, v65
	s_and_b64 s[0:1], vcc, s[0:1]
	s_andn2_b64 vcc, exec, s[0:1]
	s_cbranch_vccnz .LBB0_683
	v_sub_u32_e32 v64, s2, v64
	v_lshlrev_b32_e32 v150, 7, v64
	v_mov_b32_e32 v134, 15
	v_mov_b32_e32 v151, v67
	v_mov_b32_e32 v152, v66
.LBB0_683:
	v_add_u32_e32 v66, v67, v66
	v_mov_b32_e32 v67, v241
	v_cmp_ge_i32_e32 vcc, s2, v65
	v_add_u32_e32 v64, 0x7f, v67
	v_ashrrev_i32_e32 v64, 7, v64
	v_add_u32_e32 v64, v64, v65
	v_cmp_lt_i32_e64 s[0:1], s2, v64
	s_and_b64 s[0:1], vcc, s[0:1]
	s_andn2_b64 vcc, exec, s[0:1]
	s_cbranch_vccnz .LBB0_685
	v_sub_u32_e32 v65, s2, v65
	v_lshlrev_b32_e32 v150, 7, v65
	v_mov_b32_e32 v134, 16
	v_mov_b32_e32 v151, v67
	v_mov_b32_e32 v152, v66
.LBB0_685:
	v_readlane_b32 s0, v236, 6
	v_readlane_b32 s1, v236, 7
	v_add_u32_e32 v66, v67, v66
	v_cmp_ge_i32_e32 vcc, s2, v64
	s_nop 2
	v_mov_b32_e32 v67, v242
	v_add_u32_e32 v65, 0x7f, v67
	v_ashrrev_i32_e32 v65, 7, v65
	v_add_u32_e32 v65, v65, v64
	v_cmp_lt_i32_e64 s[0:1], s2, v65
	s_and_b64 s[0:1], vcc, s[0:1]
	s_andn2_b64 vcc, exec, s[0:1]
	s_cbranch_vccnz .LBB0_687
	v_sub_u32_e32 v64, s2, v64
	v_lshlrev_b32_e32 v150, 7, v64
	v_mov_b32_e32 v134, 17
	v_mov_b32_e32 v151, v67
	v_mov_b32_e32 v152, v66
.LBB0_687:
	v_readlane_b32 s0, v236, 2
	v_readlane_b32 s1, v236, 3
	v_add_u32_e32 v66, v67, v66
	v_cmp_ge_i32_e32 vcc, s2, v65
	s_nop 2
	v_mov_b32_e32 v67, v243
	v_add_u32_e32 v64, 0x7f, v67
	v_ashrrev_i32_e32 v64, 7, v64
	v_add_u32_e32 v64, v64, v65
	v_cmp_lt_i32_e64 s[0:1], s2, v64
	s_and_b64 s[0:1], vcc, s[0:1]
	s_andn2_b64 vcc, exec, s[0:1]
	s_cbranch_vccnz .LBB0_689
	v_sub_u32_e32 v65, s2, v65
	v_lshlrev_b32_e32 v150, 7, v65
	v_mov_b32_e32 v134, 18
	v_mov_b32_e32 v151, v67
	v_mov_b32_e32 v152, v66
.LBB0_689:
	v_readlane_b32 s0, v236, 4
	v_readlane_b32 s1, v236, 5
	v_add_u32_e32 v66, v67, v66
	v_cmp_ge_i32_e32 vcc, s2, v64
	s_nop 2
	v_mov_b32_e32 v67, v244
	v_add_u32_e32 v65, 0x7f, v67
	v_ashrrev_i32_e32 v65, 7, v65
	v_add_u32_e32 v65, v65, v64
	v_cmp_lt_i32_e64 s[0:1], s2, v65
	s_and_b64 s[0:1], vcc, s[0:1]
	s_andn2_b64 vcc, exec, s[0:1]
	s_cbranch_vccnz .LBB0_691
	v_sub_u32_e32 v64, s2, v64
	v_lshlrev_b32_e32 v150, 7, v64
	v_mov_b32_e32 v134, 19
	v_mov_b32_e32 v151, v67
	v_mov_b32_e32 v152, v66
.LBB0_691:
	v_readlane_b32 s0, v237, 62
	v_readlane_b32 s1, v237, 63
	v_add_u32_e32 v66, v67, v66
	v_cmp_ge_i32_e32 vcc, s2, v65
	s_nop 2
	v_mov_b32_e32 v67, v245
	v_add_u32_e32 v64, 0x7f, v67
	v_ashrrev_i32_e32 v64, 7, v64
	v_add_u32_e32 v64, v64, v65
	v_cmp_lt_i32_e64 s[0:1], s2, v64
	s_and_b64 s[0:1], vcc, s[0:1]
	s_andn2_b64 vcc, exec, s[0:1]
	s_cbranch_vccnz .LBB0_693
	v_sub_u32_e32 v65, s2, v65
	v_lshlrev_b32_e32 v150, 7, v65
	v_mov_b32_e32 v134, 20
	v_mov_b32_e32 v151, v67
	v_mov_b32_e32 v152, v66
.LBB0_693:
	v_readlane_b32 s0, v236, 0
	v_readlane_b32 s1, v236, 1
	v_add_u32_e32 v66, v67, v66
	v_cmp_ge_i32_e32 vcc, s2, v64
	s_nop 2
	v_mov_b32_e32 v67, v246
	v_add_u32_e32 v65, 0x7f, v67
	v_ashrrev_i32_e32 v65, 7, v65
	v_add_u32_e32 v65, v65, v64
	v_cmp_lt_i32_e64 s[0:1], s2, v65
	s_and_b64 s[0:1], vcc, s[0:1]
	s_andn2_b64 vcc, exec, s[0:1]
	s_cbranch_vccnz .LBB0_695
	v_sub_u32_e32 v64, s2, v64
	v_lshlrev_b32_e32 v150, 7, v64
	v_mov_b32_e32 v134, 21
	v_mov_b32_e32 v151, v67
	v_mov_b32_e32 v152, v66
.LBB0_695:
	v_readlane_b32 s0, v237, 60
	v_readlane_b32 s1, v237, 61
	v_add_u32_e32 v64, v67, v66
	v_cmp_ge_i32_e32 vcc, s2, v65
	s_nop 2
	v_mov_b32_e32 v66, v247
	v_add_u32_e32 v67, 0x7f, v66
	v_ashrrev_i32_e32 v67, 7, v67
	v_add_u32_e32 v67, v67, v65
	v_cmp_lt_i32_e64 s[0:1], s2, v67
	s_and_b64 s[0:1], vcc, s[0:1]
	s_andn2_b64 vcc, exec, s[0:1]
	s_cbranch_vccnz .LBB0_697
	v_sub_u32_e32 v65, s2, v65
	v_lshlrev_b32_e32 v150, 7, v65
	v_mov_b32_e32 v134, 22
	v_mov_b32_e32 v151, v66
	v_mov_b32_e32 v152, v64
.LBB0_697:
	v_readlane_b32 s0, v236, 10
	v_readlane_b32 s1, v236, 11
	v_cmp_ge_i32_e32 vcc, s2, v67
	s_nop 3
	v_mov_b32_e32 v65, v248
	v_add_u32_e32 v68, 0x7f, v65
	v_ashrrev_i32_e32 v68, 7, v68
	v_add_u32_e32 v68, v68, v67
	v_cmp_lt_i32_e64 s[0:1], s2, v68
	s_and_b64 s[0:1], vcc, s[0:1]
	s_andn2_b64 vcc, exec, s[0:1]
	s_cbranch_vccnz .LBB0_699
	v_add_u32_e32 v152, v66, v64
	v_sub_u32_e32 v64, s2, v67
	v_lshlrev_b32_e32 v150, 7, v64
	v_mov_b32_e32 v134, 23
	v_mov_b32_e32 v151, v65

.LBB0_786:
	s_or_b64 exec, exec, s[0:1]
	s_waitcnt vmcnt(8) lgkmcnt(0)
	v_mov_b32_e32 v0, 0
	s_barrier
	global_load_dwordx4 v[2:5], v0, s[92:93]
	global_load_dwordx4 v[6:9], v0, s[92:93] offset:16
	global_load_dwordx4 v[10:13], v0, s[92:93] offset:32
	global_load_dwordx4 v[14:17], v0, s[92:93] offset:48
	global_load_dwordx4 v[18:21], v0, s[96:97]
	global_load_dwordx4 v[22:25], v0, s[96:97] offset:16
	v_readlane_b32 s0, v237, 31
	v_readlane_b32 s1, v237, 32
	s_waitcnt vmcnt(5)
	v_add_u32_e32 v1, 0x7f, v2
	v_add_u32_e32 v2, 0x7f, v3
	v_add_u32_e32 v3, 0x7f, v4
	v_ashrrev_i32_e32 v1, 7, v1
	v_ashrrev_i32_e32 v2, 7, v2
	v_add_u32_e32 v4, 0x7f, v5
	v_ashrrev_i32_e32 v3, 7, v3
	v_add_u32_e32 v1, v2, v1
	s_waitcnt vmcnt(4)
	v_add_u32_e32 v5, 0x7f, v6
	v_ashrrev_i32_e32 v4, 7, v4
	v_add_u32_e32 v1, v1, v3
	v_add_u32_e32 v6, 0x7f, v7
	v_ashrrev_i32_e32 v5, 7, v5
	v_add_u32_e32 v1, v1, v4
	v_add_u32_e32 v7, 0x7f, v8
	v_ashrrev_i32_e32 v6, 7, v6
	v_add_u32_e32 v1, v1, v5
	v_add_u32_e32 v8, 0x7f, v9
	v_ashrrev_i32_e32 v7, 7, v7
	v_add_u32_e32 v1, v1, v6
	s_waitcnt vmcnt(3)
	v_add_u32_e32 v9, 0x7f, v10
	v_ashrrev_i32_e32 v8, 7, v8
	v_add_u32_e32 v1, v1, v7
	v_add_u32_e32 v10, 0x7f, v11
	v_ashrrev_i32_e32 v9, 7, v9
	v_add_u32_e32 v1, v1, v8
	v_add_u32_e32 v11, 0x7f, v12
	v_ashrrev_i32_e32 v10, 7, v10
	v_add_u32_e32 v1, v1, v9
	v_add_u32_e32 v12, 0x7f, v13
	v_ashrrev_i32_e32 v11, 7, v11
	v_add_u32_e32 v1, v1, v10
	s_waitcnt vmcnt(2)
	v_add_u32_e32 v13, 0x7f, v14
	v_ashrrev_i32_e32 v12, 7, v12
	v_add_u32_e32 v1, v1, v11
	v_add_u32_e32 v14, 0x7f, v15
	v_ashrrev_i32_e32 v13, 7, v13
	v_add_u32_e32 v1, v1, v12
	v_add_u32_e32 v15, 0x7f, v16
	v_ashrrev_i32_e32 v14, 7, v14
	v_add_u32_e32 v1, v1, v13
	v_add_u32_e32 v16, 0x7f, v17
	v_ashrrev_i32_e32 v15, 7, v15
	v_add_u32_e32 v1, v1, v14
	s_waitcnt vmcnt(1)
	v_add_u32_e32 v17, 0x7f, v18
	v_ashrrev_i32_e32 v16, 7, v16
	v_add_u32_e32 v1, v1, v15
	v_add_u32_e32 v18, 0x7f, v19
	v_ashrrev_i32_e32 v17, 7, v17
	v_add_u32_e32 v1, v1, v16
	v_add_u32_e32 v19, 0x7f, v20
	v_ashrrev_i32_e32 v18, 7, v18
	v_add_u32_e32 v1, v1, v17
	v_add_u32_e32 v20, 0x7f, v21
	v_ashrrev_i32_e32 v19, 7, v19
	v_add_u32_e32 v1, v1, v18
	s_waitcnt vmcnt(0)
	v_add_u32_e32 v21, 0x7f, v22
	v_ashrrev_i32_e32 v20, 7, v20
	v_add_u32_e32 v1, v1, v19
	v_add_u32_e32 v22, 0x7f, v23
	v_ashrrev_i32_e32 v21, 7, v21
	v_add_u32_e32 v1, v1, v20
	v_add_u32_e32 v23, 0x7f, v24
	v_ashrrev_i32_e32 v22, 7, v22
	v_add_u32_e32 v1, v1, v21
	v_add_u32_e32 v24, 0x7f, v25
	v_ashrrev_i32_e32 v23, 7, v23
	v_add_u32_e32 v1, v1, v22
	v_ashrrev_i32_e32 v24, 7, v24
	v_add_u32_e32 v1, v1, v23
	v_add_u32_e32 v1, v1, v24
	v_lshlrev_b32_e32 v129, 3, v1
	v_cmp_ge_i32_e32 vcc, s0, v129
	v_mov_b32_e32 v8, v128
	s_cbranch_vccnz .LBB0_873
	global_load_dword v238, v0, s[92:93] offset:52
	global_load_dword v239, v0, s[92:93] offset:56
	global_load_dword v240, v0, s[92:93] offset:60
	global_load_dword v241, v0, s[92:93] offset:64
	global_load_dword v242, v0, s[92:93] offset:68
	global_load_dword v243, v0, s[92:93] offset:72
	global_load_dword v244, v0, s[92:93] offset:76
	global_load_dword v245, v0, s[92:93] offset:80
	global_load_dword v246, v0, s[92:93] offset:84
	global_load_dword v247, v0, s[92:93] offset:88
	global_load_dword v248, v0, s[92:93] offset:92
	global_load_dword v9, v0, s[92:93] offset:48
	global_load_dwordx4 v[4:7], v0, s[92:93] offset:16
	global_load_dwordx4 v[10:13], v0, s[92:93]
	v_readlane_b32 s0, v237, 31
	global_load_dwordx4 v[0:3], v0, s[92:93] offset:32
	s_ashr_i32 s16, s0, 3
	v_readlane_b32 s1, v237, 32
	s_cmp_gt_i32 s16, -1
	s_cselect_b64 s[0:1], -1, 0
	s_lshl_b32 s4, s16, 7
	s_waitcnt vmcnt(2)
	v_readfirstlane_b32 s10, v4
	s_waitcnt vmcnt(1)
	v_readfirstlane_b32 s7, v10
	s_add_i32 s2, s7, 0x7f
	s_ashr_i32 s9, s2, 7
	s_cmp_lt_i32 s16, s9
	s_cselect_b64 s[2:3], -1, 0
	s_and_b64 s[0:1], s[0:1], s[2:3]
	v_readfirstlane_b32 s5, v11
	s_and_b64 s[0:1], s[0:1], exec
	s_cselect_b32 s4, s4, 0
	s_cselect_b32 s11, s7, 0
	s_add_i32 s0, s5, 0x7f
	s_ashr_i32 s2, s0, 7
	s_cmp_ge_i32 s16, s9
	s_cselect_b64 s[0:1], -1, 0
	s_add_i32 s12, s2, s9
	s_cmp_lt_i32 s16, s12
	s_cselect_b64 s[2:3], -1, 0
	s_and_b64 s[2:3], s[0:1], s[2:3]
	s_sub_i32 s0, s16, s9
	s_lshl_b32 s9, s0, 7
	v_readfirstlane_b32 s6, v12
	s_and_b64 s[0:1], s[2:3], exec
	s_cselect_b32 s9, s9, s4
	s_cselect_b32 s13, s7, 0
	s_cselect_b32 s11, s5, s11
	s_add_i32 s0, s6, 0x7f
	s_add_i32 s7, s5, s7
	s_ashr_i32 s4, s0, 7
	s_cmp_ge_i32 s16, s12
	s_cselect_b64 s[0:1], -1, 0
	s_add_i32 s14, s4, s12
	s_cmp_lt_i32 s16, s14
	s_cselect_b64 s[4:5], -1, 0
	s_and_b64 s[4:5], s[0:1], s[4:5]
	s_sub_i32 s0, s16, s12
	s_lshl_b32 s12, s0, 7
	v_readfirstlane_b32 s8, v13
	s_and_b64 s[0:1], s[4:5], exec
	s_cselect_b32 s9, s12, s9
	s_cselect_b32 s11, s6, s11
	s_cselect_b32 s12, s7, s13
	s_add_i32 s0, s8, 0x7f
	s_add_i32 s13, s6, s7
	s_ashr_i32 s6, s0, 7
	s_cmp_ge_i32 s16, s14
	s_cselect_b64 s[0:1], -1, 0
	s_add_i32 s15, s6, s14
	s_cmp_lt_i32 s16, s15
	s_cselect_b64 s[6:7], -1, 0
	s_and_b64 s[6:7], s[0:1], s[6:7]
	s_sub_i32 s0, s16, s14
	s_lshl_b32 s14, s0, 7
	s_and_b64 s[0:1], s[6:7], exec
	s_cselect_b32 s14, s14, s9
	s_cselect_b32 s12, s13, s12
	s_cselect_b32 s11, s8, s11
	s_add_i32 s0, s10, 0x7f
	s_add_i32 s13, s8, s13
	s_ashr_i32 s8, s0, 7
	s_cmp_ge_i32 s16, s15
	s_cselect_b64 s[0:1], -1, 0
	s_add_i32 s18, s8, s15
	v_add_u32_e32 v4, 0x7f, v5
	s_cmp_lt_i32 s16, s18
	v_ashrrev_i32_e32 v4, 7, v4
	v_add_u32_e32 v11, 0x7f, v6
	s_cselect_b64 s[8:9], -1, 0
	v_add_u32_e32 v10, s18, v4
	v_ashrrev_i32_e32 v11, 7, v11
	v_add_u32_e32 v13, 0x7f, v7
	s_and_b64 s[38:39], s[0:1], s[8:9]
	s_sub_i32 s0, s16, s15
	v_add_u32_e32 v12, v11, v10
	v_ashrrev_i32_e32 v13, 7, v13
	s_waitcnt vmcnt(0)
	v_add_u32_e32 v15, 0x7f, v0
	s_lshl_b32 s8, s0, 7
	v_add_u32_e32 v14, v13, v12
	v_ashrrev_i32_e32 v15, 7, v15
	v_add_u32_e32 v17, 0x7f, v1
	s_and_b64 s[0:1], s[38:39], exec
	v_add_u32_e32 v16, v15, v14
	v_ashrrev_i32_e32 v17, 7, v17
	v_add_u32_e32 v19, 0x7f, v2
	s_cselect_b32 s14, s8, s14
	s_cselect_b32 s17, s10, s11
	s_cselect_b32 s11, s13, s12
	s_add_i32 s10, s10, s13
	v_add_u32_e32 v18, v17, v16
	v_ashrrev_i32_e32 v19, 7, v19
	v_add_u32_e32 v21, 0x7f, v3
	v_add_u32_e32 v4, s10, v5
	v_add_u32_e32 v20, v19, v18
	v_ashrrev_i32_e32 v21, 7, v21
	s_cmp_ge_i32 s16, s18
	v_add_u32_e32 v11, v6, v4
	v_add_u32_e32 v23, v21, v20
	v_add_u32_e32 v21, 0x7f, v9
	s_cselect_b64 s[0:1], -1, 0
	v_cmp_lt_i32_e32 vcc, s16, v10
	s_sub_i32 s8, s16, s18
	v_add_u32_e32 v13, v7, v11
	v_ashrrev_i32_e32 v21, 7, v21
	s_and_b64 s[0:1], s[0:1], vcc
	s_lshl_b32 s12, s8, 7
	v_add_u32_e32 v15, v0, v13
	v_add_u32_e32 v21, v21, v23
	s_and_b64 s[8:9], s[0:1], exec
	v_add_u32_e32 v17, v1, v15
	v_cmp_ge_i32_e32 vcc, s16, v23
	v_cmp_lt_i32_e64 s[36:37], s16, v21
	s_cselect_b32 s40, s12, s14
	s_cselect_b32 s33, s10, s11
	v_add_u32_e32 v19, v2, v17
	s_and_b64 s[36:37], vcc, s[36:37]
	v_cmp_ge_i32_e64 s[8:9], s16, v10
	v_cmp_lt_i32_e64 s[10:11], s16, v12
	v_cmp_ge_i32_e64 s[12:13], s16, v12
	v_cmp_lt_i32_e64 s[14:15], s16, v14
	v_cmp_ge_i32_e64 s[18:19], s16, v14
	v_cmp_lt_i32_e64 s[20:21], s16, v16
	v_cmp_ge_i32_e64 s[22:23], s16, v16
	v_cmp_lt_i32_e64 s[24:25], s16, v18
	v_cmp_ge_i32_e64 s[26:27], s16, v18
	v_cmp_lt_i32_e64 s[28:29], s16, v20
	v_cmp_ge_i32_e64 s[30:31], s16, v20
	v_cmp_lt_i32_e64 s[34:35], s16, v23
	v_add_u32_e32 v22, v3, v19
	s_andn2_b64 vcc, exec, s[36:37]
	s_cbranch_vccnz .LBB0_789
	v_sub_u32_e32 v0, s16, v23
	v_lshlrev_b32_e32 v138, 7, v0
	v_mov_b32_e32 v130, 12
	v_mov_b32_e32 v139, v9
	v_mov_b32_e32 v0, v22
	s_branch .LBB0_790

.LBB0_790:
	v_mov_b32_e32 v1, 0
	v_mov_b32_e32 v4, v238
	v_cmp_ge_i32_e32 vcc, s16, v21
	v_add_u32_e32 v5, v9, v22
	v_add_u32_e32 v2, 0x7f, v4
	v_ashrrev_i32_e32 v2, 7, v2
	v_add_u32_e32 v3, v2, v21
	v_cmp_lt_i32_e64 s[0:1], s16, v3
	s_and_b64 s[0:1], vcc, s[0:1]
	s_andn2_b64 vcc, exec, s[0:1]
	s_cbranch_vccnz .LBB0_792
	v_sub_u32_e32 v0, s16, v21
	v_lshlrev_b32_e32 v138, 7, v0
	v_mov_b32_e32 v130, 13
	v_mov_b32_e32 v139, v4
	v_mov_b32_e32 v0, v5
.LBB0_792:
	v_mov_b32_e32 v2, v239
	v_cmp_ge_i32_e32 vcc, s16, v3
	v_add_u32_e32 v6, v4, v5
	v_add_u32_e32 v1, 0x7f, v2
	v_ashrrev_i32_e32 v1, 7, v1
	v_add_u32_e32 v1, v1, v3
	v_cmp_lt_i32_e64 s[0:1], s16, v1
	s_and_b64 s[0:1], vcc, s[0:1]
	s_andn2_b64 vcc, exec, s[0:1]
	s_cbranch_vccnz .LBB0_794
	v_sub_u32_e32 v0, s16, v3
	v_lshlrev_b32_e32 v138, 7, v0
	v_mov_b32_e32 v130, 14
	v_mov_b32_e32 v139, v2
	v_mov_b32_e32 v0, v6
.LBB0_794:
	v_readlane_b32 s0, v236, 8
	v_mov_b32_e32 v3, 0
	v_readlane_b32 s1, v236, 9
	v_cmp_ge_i32_e32 vcc, s16, v1
	v_add_u32_e32 v2, v2, v6
	s_nop 2
	v_mov_b32_e32 v5, v240
	v_add_u32_e32 v4, 0x7f, v5
	v_ashrrev_i32_e32 v4, 7, v4
	v_add_u32_e32 v4, v4, v1
	v_cmp_lt_i32_e64 s[0:1], s16, v4
	s_and_b64 s[0:1], vcc, s[0:1]
	s_andn2_b64 vcc, exec, s[0:1]
	s_cbranch_vccnz .LBB0_796
	v_sub_u32_e32 v0, s16, v1
	v_lshlrev_b32_e32 v138, 7, v0
	v_mov_b32_e32 v130, 15
	v_mov_b32_e32 v139, v5
	v_mov_b32_e32 v0, v2
.LBB0_796:
	v_mov_b32_e32 v3, v241
	v_cmp_ge_i32_e32 vcc, s16, v4
	v_add_u32_e32 v6, v5, v2
	v_add_u32_e32 v1, 0x7f, v3
	v_ashrrev_i32_e32 v1, 7, v1
	v_add_u32_e32 v1, v1, v4
	v_cmp_lt_i32_e64 s[0:1], s16, v1
	s_and_b64 s[0:1], vcc, s[0:1]
	s_andn2_b64 vcc, exec, s[0:1]
	s_cbranch_vccnz .LBB0_798
	v_sub_u32_e32 v0, s16, v4
	v_lshlrev_b32_e32 v138, 7, v0
	v_mov_b32_e32 v130, 16
	v_mov_b32_e32 v139, v3
	v_mov_b32_e32 v0, v6
.LBB0_798:
	v_readlane_b32 s0, v236, 6
	v_mov_b32_e32 v5, 0
	v_readlane_b32 s1, v236, 7
	v_cmp_ge_i32_e32 vcc, s16, v1
	v_add_u32_e32 v6, v3, v6
	s_nop 2
	v_mov_b32_e32 v4, v242
	v_add_u32_e32 v2, 0x7f, v4
	v_ashrrev_i32_e32 v2, 7, v2
	v_add_u32_e32 v2, v2, v1
	v_cmp_lt_i32_e64 s[0:1], s16, v2
	s_and_b64 s[0:1], vcc, s[0:1]
	s_andn2_b64 vcc, exec, s[0:1]
	s_cbranch_vccnz .LBB0_800
	v_sub_u32_e32 v0, s16, v1
	v_lshlrev_b32_e32 v138, 7, v0
	v_mov_b32_e32 v130, 17
	v_mov_b32_e32 v139, v4
	v_mov_b32_e32 v0, v6
.LBB0_800:
	v_readlane_b32 s0, v236, 2
	v_readlane_b32 s1, v236, 3
	v_cmp_ge_i32_e32 vcc, s16, v2
	v_add_u32_e32 v6, v4, v6
	s_nop 2
	v_mov_b32_e32 v3, v243
	v_add_u32_e32 v1, 0x7f, v3
	v_ashrrev_i32_e32 v1, 7, v1
	v_add_u32_e32 v1, v1, v2
	v_cmp_lt_i32_e64 s[0:1], s16, v1
	s_and_b64 s[0:1], vcc, s[0:1]
	s_andn2_b64 vcc, exec, s[0:1]
	s_cbranch_vccnz .LBB0_802
	v_sub_u32_e32 v0, s16, v2
	v_lshlrev_b32_e32 v138, 7, v0
	v_mov_b32_e32 v130, 18
	v_mov_b32_e32 v139, v3
	v_mov_b32_e32 v0, v6
.LBB0_802:
	v_readlane_b32 s0, v236, 4
	v_mov_b32_e32 v4, 0
	v_readlane_b32 s1, v236, 5
	v_cmp_ge_i32_e32 vcc, s16, v1
	v_add_u32_e32 v3, v3, v6
	s_nop 2
	v_mov_b32_e32 v5, v244
	v_add_u32_e32 v2, 0x7f, v5
	v_ashrrev_i32_e32 v2, 7, v2
	v_add_u32_e32 v2, v2, v1
	v_cmp_lt_i32_e64 s[0:1], s16, v2
	s_and_b64 s[0:1], vcc, s[0:1]
	s_andn2_b64 vcc, exec, s[0:1]
	s_cbranch_vccnz .LBB0_804
	v_sub_u32_e32 v0, s16, v1
	v_lshlrev_b32_e32 v138, 7, v0
	v_mov_b32_e32 v130, 19
	v_mov_b32_e32 v139, v5
	v_mov_b32_e32 v0, v3
.LBB0_804:
	v_readlane_b32 s0, v237, 62
	v_readlane_b32 s1, v237, 63
	v_cmp_ge_i32_e32 vcc, s16, v2
	v_add_u32_e32 v6, v5, v3
	s_nop 2
	v_mov_b32_e32 v4, v245
	v_add_u32_e32 v1, 0x7f, v4
	v_ashrrev_i32_e32 v1, 7, v1
	v_add_u32_e32 v1, v1, v2
	v_cmp_lt_i32_e64 s[0:1], s16, v1
	s_and_b64 s[0:1], vcc, s[0:1]
	s_andn2_b64 vcc, exec, s[0:1]
	s_cbranch_vccnz .LBB0_806
	v_sub_u32_e32 v0, s16, v2
	v_lshlrev_b32_e32 v138, 7, v0
	v_mov_b32_e32 v130, 20
	v_mov_b32_e32 v139, v4
	v_mov_b32_e32 v0, v6
.LBB0_806:
	v_readlane_b32 s0, v236, 0
	v_mov_b32_e32 v2, 0
	v_readlane_b32 s1, v236, 1
	v_cmp_ge_i32_e32 vcc, s16, v1
	v_add_u32_e32 v4, v4, v6
	s_nop 2
	v_mov_b32_e32 v5, v246
	v_add_u32_e32 v3, 0x7f, v5
	v_ashrrev_i32_e32 v3, 7, v3
	v_add_u32_e32 v3, v3, v1
	v_cmp_lt_i32_e64 s[0:1], s16, v3
	s_and_b64 s[0:1], vcc, s[0:1]
	s_andn2_b64 vcc, exec, s[0:1]
	s_cbranch_vccnz .LBB0_808
	v_sub_u32_e32 v0, s16, v1
	v_lshlrev_b32_e32 v138, 7, v0
	v_mov_b32_e32 v130, 21
	v_mov_b32_e32 v139, v5
	v_mov_b32_e32 v0, v4
.LBB0_808:
	v_readlane_b32 s0, v237, 60
	v_readlane_b32 s1, v237, 61
	v_cmp_ge_i32_e32 vcc, s16, v3
	v_add_u32_e32 v4, v5, v4
	s_nop 2
	v_mov_b32_e32 v1, v247
	v_add_u32_e32 v2, 0x7f, v1
	v_ashrrev_i32_e32 v2, 7, v2
	v_add_u32_e32 v2, v2, v3
	v_cmp_lt_i32_e64 s[0:1], s16, v2
	s_and_b64 s[0:1], vcc, s[0:1]
	s_andn2_b64 vcc, exec, s[0:1]
	s_cbranch_vccnz .LBB0_810
	v_sub_u32_e32 v0, s16, v3
	v_lshlrev_b32_e32 v138, 7, v0
	v_mov_b32_e32 v130, 22
	v_mov_b32_e32 v139, v1
	v_mov_b32_e32 v0, v4
.LBB0_810:
	v_readlane_b32 s0, v236, 10
	v_mov_b32_e32 v133, 0
	v_readlane_b32 s1, v236, 11
	v_cmp_ge_i32_e32 vcc, s16, v2
	v_readlane_b32 s82, v236, 8
	v_readlane_b32 s83, v236, 9
	s_nop 1
	v_mov_b32_e32 v3, v248
	v_add_u32_e32 v5, 0x7f, v3
	v_ashrrev_i32_e32 v5, 7, v5
	v_add_u32_e32 v5, v5, v2
	v_cmp_lt_i32_e64 s[0:1], s16, v5
	s_and_b64 s[0:1], vcc, s[0:1]
	s_andn2_b64 vcc, exec, s[0:1]
	s_cbranch_vccnz .LBB0_812
	v_add_u32_e32 v0, v1, v4
	v_sub_u32_e32 v1, s16, v2
	v_lshlrev_b32_e32 v138, 7, v1
	v_mov_b32_e32 v130, 23
	v_mov_b32_e32 v139, v3

.LBB0_814:
	global_load_dword v238, v133, s[92:93] offset:52
	global_load_dword v239, v133, s[92:93] offset:56
	global_load_dword v240, v133, s[92:93] offset:60
	global_load_dword v241, v133, s[92:93] offset:64
	global_load_dword v242, v133, s[92:93] offset:68
	global_load_dword v243, v133, s[92:93] offset:72
	global_load_dword v244, v133, s[92:93] offset:76
	global_load_dword v245, v133, s[92:93] offset:80
	global_load_dword v246, v133, s[92:93] offset:84
	global_load_dword v247, v133, s[92:93] offset:88
	global_load_dword v248, v133, s[92:93] offset:92
	global_load_dwordx4 v[72:75], v133, s[92:93]
	global_load_dwordx4 v[68:71], v133, s[92:93] offset:16
	global_load_dwordx4 v[64:67], v133, s[92:93] offset:32
	global_load_dword v76, v133, s[92:93] offset:48
	v_readlane_b32 s8, v237, 56
	v_readlane_b32 s10, v237, 58
	v_readlane_b32 s11, v237, 59
	s_add_i32 s17, s16, s10
	v_cmp_lt_i32_e64 s[10:11], s17, v129
	s_and_b64 s[0:1], s[10:11], exec
	s_cselect_b32 s33, s17, s16
	s_ashr_i32 s2, s33, 3
	s_cmp_gt_i32 s2, -1
	s_cselect_b64 s[0:1], -1, 0
	s_lshl_b32 s12, s2, 7
	v_readlane_b32 s9, v237, 57
	v_cmp_ge_i32_e64 s[8:9], s17, v129
	s_waitcnt vmcnt(3)
	v_add_u32_e32 v77, 0x7f, v72
	v_add_u32_e32 v79, 0x7f, v73
	v_add_u32_e32 v80, 0x7f, v74
	v_ashrrev_i32_e32 v96, 7, v77
	v_ashrrev_i32_e32 v77, 7, v79
	v_add_u32_e32 v81, 0x7f, v75
	v_ashrrev_i32_e32 v79, 7, v80
	v_add_u32_e32 v99, v77, v96
	s_waitcnt vmcnt(2)
	v_add_u32_e32 v82, 0x7f, v68
	v_ashrrev_i32_e32 v80, 7, v81
	v_add_u32_e32 v98, v79, v99
	v_add_u32_e32 v83, 0x7f, v69
	v_ashrrev_i32_e32 v81, 7, v82
	v_add_u32_e32 v97, v80, v98
	v_add_u32_e32 v84, 0x7f, v70
	v_ashrrev_i32_e32 v82, 7, v83
	v_add_u32_e32 v95, v81, v97
	v_add_u32_e32 v78, v73, v72
	v_add_u32_e32 v85, 0x7f, v71
	v_ashrrev_i32_e32 v84, 7, v84
	v_add_u32_e32 v94, v82, v95
	s_waitcnt vmcnt(1)
	v_add_u32_e32 v86, 0x7f, v64
	s_waitcnt vmcnt(0)
	v_add_u32_e32 v91, 0x7f, v76
	v_add_u32_e32 v88, v74, v78
	v_ashrrev_i32_e32 v92, 7, v85
	v_add_u32_e32 v93, v84, v94
	v_add_u32_e32 v87, 0x7f, v65
	v_add_u32_e32 v89, 0x7f, v66
	v_add_u32_e32 v90, 0x7f, v67
	v_ashrrev_i32_e32 v86, 7, v86
	v_ashrrev_i32_e32 v103, 7, v91
	v_add_u32_e32 v91, v75, v88
	v_add_u32_e32 v92, v92, v93
	v_ashrrev_i32_e32 v100, 7, v87
	v_ashrrev_i32_e32 v101, 7, v89
	v_ashrrev_i32_e32 v102, 7, v90
	v_add_u32_e32 v90, v68, v91
	v_add_u32_e32 v89, v86, v92
	v_add_u32_e32 v87, v69, v90
	v_add_u32_e32 v86, v100, v89
	v_add_u32_e32 v85, v70, v87
	v_add_u32_e32 v84, v101, v86
	v_cmp_lt_i32_e32 vcc, s2, v96
	v_add_u32_e32 v83, v71, v85
	v_add_u32_e32 v100, v102, v84
	s_and_b64 s[58:59], s[0:1], vcc
	v_add_u32_e32 v82, v64, v83
	v_add_u32_e32 v77, v103, v100
	s_and_b64 s[0:1], s[58:59], exec
	v_add_u32_e32 v81, v65, v82
	v_cmp_ge_i32_e32 vcc, s2, v100
	v_cmp_lt_i32_e64 s[60:61], s2, v77
	s_cselect_b32 s74, s12, 0
	v_add_u32_e32 v80, v66, v81
	s_and_b64 s[60:61], vcc, s[60:61]
	v_cmp_ge_i32_e64 s[52:53], s2, v96
	v_cmp_lt_i32_e64 s[56:57], s2, v99
	v_cmp_ge_i32_e64 s[48:49], s2, v99
	v_cmp_lt_i32_e64 s[54:55], s2, v98
	v_cmp_ge_i32_e64 s[46:47], s2, v98
	v_cmp_lt_i32_e64 s[50:51], s2, v97
	v_cmp_ge_i32_e64 s[42:43], s2, v97
	v_cmp_lt_i32_e64 s[44:45], s2, v95
	v_cmp_ge_i32_e64 s[38:39], s2, v95
	v_cmp_lt_i32_e64 s[40:41], s2, v94
	v_cmp_ge_i32_e64 s[34:35], s2, v94
	v_cmp_lt_i32_e64 s[36:37], s2, v93
	v_cmp_ge_i32_e64 s[28:29], s2, v93
	v_cmp_lt_i32_e64 s[30:31], s2, v92
	v_cmp_ge_i32_e64 s[24:25], s2, v92
	v_cmp_lt_i32_e64 s[26:27], s2, v89
	v_cmp_ge_i32_e64 s[20:21], s2, v89
	v_cmp_lt_i32_e64 s[22:23], s2, v86
	v_cmp_ge_i32_e64 s[14:15], s2, v86
	v_cmp_lt_i32_e64 s[18:19], s2, v84
	v_cmp_ge_i32_e64 s[0:1], s2, v84
	v_cmp_lt_i32_e64 s[12:13], s2, v100
	s_andn2_b64 vcc, exec, s[60:61]
	v_add_u32_e32 v79, v67, v80
	s_cbranch_vccnz .LBB0_816
	v_sub_u32_e32 v64, s2, v100
	v_lshlrev_b32_e32 v145, 7, v64
	v_mov_b32_e32 v146, 12
	v_mov_b32_e32 v147, v76
	v_mov_b32_e32 v64, v79
	s_branch .LBB0_817

.LBB0_817:
	v_mov_b32_e32 v67, v238
	v_cmp_ge_i32_e32 vcc, s2, v77
	v_readlane_b32 s18, v237, 27
	s_mov_b64 s[12:13], s[82:83]
	v_add_u32_e32 v66, v76, v79
	v_readlane_b32 s19, v237, 28
	v_add_u32_e32 v65, 0x7f, v67
	v_ashrrev_i32_e32 v65, 7, v65
	v_add_u32_e32 v65, v65, v77
	v_cmp_lt_i32_e64 s[0:1], s2, v65
	s_and_b64 s[0:1], vcc, s[0:1]
	s_andn2_b64 vcc, exec, s[0:1]
	s_cbranch_vccnz .LBB0_819
	v_sub_u32_e32 v64, s2, v77
	v_lshlrev_b32_e32 v145, 7, v64
	v_mov_b32_e32 v146, 13
	v_mov_b32_e32 v147, v67
	v_mov_b32_e32 v64, v66
.LBB0_819:
	v_mov_b32_e32 v68, v239
	v_add_u32_e32 v66, v67, v66
	v_cmp_ge_i32_e32 vcc, s2, v65
	v_add_u32_e32 v67, 0x7f, v68
	v_ashrrev_i32_e32 v67, 7, v67
	v_add_u32_e32 v67, v67, v65
	v_cmp_lt_i32_e64 s[0:1], s2, v67
	s_and_b64 s[0:1], vcc, s[0:1]
	s_andn2_b64 vcc, exec, s[0:1]
	s_cbranch_vccnz .LBB0_821
	v_sub_u32_e32 v64, s2, v65
	v_lshlrev_b32_e32 v145, 7, v64
	v_mov_b32_e32 v146, 14
	v_mov_b32_e32 v147, v68
	v_mov_b32_e32 v64, v66
.LBB0_821:
	v_add_u32_e32 v65, v68, v66
	v_mov_b32_e32 v68, v240
	v_cmp_ge_i32_e32 vcc, s2, v67
	v_add_u32_e32 v66, 0x7f, v68
	v_ashrrev_i32_e32 v66, 7, v66
	v_add_u32_e32 v66, v66, v67
	v_cmp_lt_i32_e64 s[0:1], s2, v66
	s_and_b64 s[0:1], vcc, s[0:1]
	s_andn2_b64 vcc, exec, s[0:1]
	s_cbranch_vccnz .LBB0_823
	v_sub_u32_e32 v64, s2, v67
	v_lshlrev_b32_e32 v145, 7, v64
	v_mov_b32_e32 v146, 15
	v_mov_b32_e32 v147, v68
	v_mov_b32_e32 v64, v65
.LBB0_823:
	v_add_u32_e32 v67, v68, v65
	v_mov_b32_e32 v68, v241
	v_cmp_ge_i32_e32 vcc, s2, v66
	v_add_u32_e32 v65, 0x7f, v68
	v_ashrrev_i32_e32 v65, 7, v65
	v_add_u32_e32 v65, v65, v66
	v_cmp_lt_i32_e64 s[0:1], s2, v65
	s_and_b64 s[0:1], vcc, s[0:1]
	s_andn2_b64 vcc, exec, s[0:1]
	s_cbranch_vccnz .LBB0_825
	v_sub_u32_e32 v64, s2, v66
	v_lshlrev_b32_e32 v145, 7, v64
	v_mov_b32_e32 v146, 16
	v_mov_b32_e32 v147, v68
	v_mov_b32_e32 v64, v67
.LBB0_825:
	v_readlane_b32 s0, v236, 6
	v_readlane_b32 s1, v236, 7
	v_add_u32_e32 v67, v68, v67
	v_cmp_ge_i32_e32 vcc, s2, v65
	s_nop 2
	v_mov_b32_e32 v68, v242
	v_add_u32_e32 v66, 0x7f, v68
	v_ashrrev_i32_e32 v66, 7, v66
	v_add_u32_e32 v66, v66, v65
	v_cmp_lt_i32_e64 s[0:1], s2, v66
	s_and_b64 s[0:1], vcc, s[0:1]
	s_andn2_b64 vcc, exec, s[0:1]
	s_cbranch_vccnz .LBB0_827
	v_sub_u32_e32 v64, s2, v65
	v_lshlrev_b32_e32 v145, 7, v64
	v_mov_b32_e32 v146, 17
	v_mov_b32_e32 v147, v68
	v_mov_b32_e32 v64, v67
.LBB0_827:
	v_readlane_b32 s0, v236, 2
	v_readlane_b32 s1, v236, 3
	v_add_u32_e32 v67, v68, v67
	v_cmp_ge_i32_e32 vcc, s2, v66
	s_nop 2
	v_mov_b32_e32 v68, v243
	v_add_u32_e32 v65, 0x7f, v68
	v_ashrrev_i32_e32 v65, 7, v65
	v_add_u32_e32 v65, v65, v66
	v_cmp_lt_i32_e64 s[0:1], s2, v65
	s_and_b64 s[0:1], vcc, s[0:1]
	s_andn2_b64 vcc, exec, s[0:1]
	s_cbranch_vccnz .LBB0_829
	v_sub_u32_e32 v64, s2, v66
	v_lshlrev_b32_e32 v145, 7, v64
	v_mov_b32_e32 v146, 18
	v_mov_b32_e32 v147, v68
	v_mov_b32_e32 v64, v67
.LBB0_829:
	v_readlane_b32 s0, v236, 4
	v_readlane_b32 s1, v236, 5
	v_add_u32_e32 v67, v68, v67
	v_cmp_ge_i32_e32 vcc, s2, v65
	s_nop 2
	v_mov_b32_e32 v68, v244
	v_add_u32_e32 v66, 0x7f, v68
	v_ashrrev_i32_e32 v66, 7, v66
	v_add_u32_e32 v66, v66, v65
	v_cmp_lt_i32_e64 s[0:1], s2, v66
	s_and_b64 s[0:1], vcc, s[0:1]
	s_andn2_b64 vcc, exec, s[0:1]
	s_cbranch_vccnz .LBB0_831
	v_sub_u32_e32 v64, s2, v65
	v_lshlrev_b32_e32 v145, 7, v64
	v_mov_b32_e32 v146, 19
	v_mov_b32_e32 v147, v68
	v_mov_b32_e32 v64, v67
.LBB0_831:
	v_readlane_b32 s0, v237, 62
	v_readlane_b32 s1, v237, 63
	v_add_u32_e32 v67, v68, v67
	v_cmp_ge_i32_e32 vcc, s2, v66
	s_nop 2
	v_mov_b32_e32 v68, v245
	v_add_u32_e32 v65, 0x7f, v68
	v_ashrrev_i32_e32 v65, 7, v65
	v_add_u32_e32 v65, v65, v66
	v_cmp_lt_i32_e64 s[0:1], s2, v65
	s_and_b64 s[0:1], vcc, s[0:1]
	s_andn2_b64 vcc, exec, s[0:1]
	s_cbranch_vccnz .LBB0_833
	v_sub_u32_e32 v64, s2, v66
	v_lshlrev_b32_e32 v145, 7, v64
	v_mov_b32_e32 v146, 20
	v_mov_b32_e32 v147, v68
	v_mov_b32_e32 v64, v67
.LBB0_833:
	v_readlane_b32 s0, v236, 0
	v_readlane_b32 s1, v236, 1
	v_add_u32_e32 v67, v68, v67
	v_cmp_ge_i32_e32 vcc, s2, v65
	s_nop 2
	v_mov_b32_e32 v68, v246
	v_add_u32_e32 v66, 0x7f, v68
	v_ashrrev_i32_e32 v66, 7, v66
	v_add_u32_e32 v66, v66, v65
	v_cmp_lt_i32_e64 s[0:1], s2, v66
	s_and_b64 s[0:1], vcc, s[0:1]
	s_andn2_b64 vcc, exec, s[0:1]
	s_cbranch_vccnz .LBB0_835
	v_sub_u32_e32 v64, s2, v65
	v_lshlrev_b32_e32 v145, 7, v64
	v_mov_b32_e32 v146, 21
	v_mov_b32_e32 v147, v68
	v_mov_b32_e32 v64, v67
.LBB0_835:
	v_readlane_b32 s0, v237, 60
	v_readlane_b32 s1, v237, 61
	v_add_u32_e32 v65, v68, v67
	v_cmp_ge_i32_e32 vcc, s2, v66
	s_nop 2
	v_mov_b32_e32 v67, v247
	v_add_u32_e32 v68, 0x7f, v67
	v_ashrrev_i32_e32 v68, 7, v68
	v_add_u32_e32 v68, v68, v66
	v_cmp_lt_i32_e64 s[0:1], s2, v68
	s_and_b64 s[0:1], vcc, s[0:1]
	s_andn2_b64 vcc, exec, s[0:1]
	s_cbranch_vccnz .LBB0_837
	v_sub_u32_e32 v64, s2, v66
	v_lshlrev_b32_e32 v145, 7, v64
	v_mov_b32_e32 v146, 22
	v_mov_b32_e32 v147, v67
	v_mov_b32_e32 v64, v65
.LBB0_837:
	v_readlane_b32 s0, v236, 10
	v_readlane_b32 s1, v236, 11
	v_cmp_ge_i32_e32 vcc, s2, v68
	s_nop 3
	v_mov_b32_e32 v66, v248
	v_add_u32_e32 v69, 0x7f, v66
	v_ashrrev_i32_e32 v69, 7, v69
	v_add_u32_e32 v69, v69, v68
	v_cmp_lt_i32_e64 s[0:1], s2, v69
	s_and_b64 s[0:1], vcc, s[0:1]
	s_andn2_b64 vcc, exec, s[0:1]
	s_cbranch_vccnz .LBB0_839
	v_add_u32_e32 v64, v67, v65
	v_sub_u32_e32 v65, s2, v68
	v_lshlrev_b32_e32 v145, 7, v65
	v_mov_b32_e32 v146, 23
	v_mov_b32_e32 v147, v66

.LBB0_1770:
	s_or_b64 exec, exec, s[0:1]
	v_readlane_b32 s0, v237, 56
	s_waitcnt lgkmcnt(0)
	v_mov_b32_e32 v0, 0x3d00000
	v_readlane_b32 s1, v237, 57
	s_barrier
	s_nop 3
	global_load_dwordx4 v[2:5], v0, s[0:1] offset:128
	global_load_dwordx4 v[6:9], v0, s[0:1] offset:192
	v_readlane_b32 s2, v237, 58
	v_readlane_b32 s3, v237, 59
	s_add_u32 s2, s0, 0x3d00080
	v_mov_b32_e32 v0, 0
	s_addc_u32 s3, s1, 0
	s_nop 1
	global_load_dwordx4 v[10:13], v0, s[2:3] offset:16
	global_load_dwordx4 v[14:17], v0, s[2:3] offset:32
	global_load_dwordx4 v[18:21], v0, s[2:3] offset:48
	s_add_u32 s86, s0, 0x3d000b4
	s_addc_u32 s87, s1, 0
	s_add_u32 s62, s0, 0x3d000b8
	s_addc_u32 s63, s1, 0
	s_add_u32 s64, s0, 0x3d000bc
	s_addc_u32 s65, s1, 0
	s_add_u32 s66, s0, 0x3d000c0
	s_addc_u32 s67, s1, 0
	global_load_dwordx4 v[22:25], v0, s[66:67] offset:16
	s_add_u32 s68, s0, 0x3d000c4
	s_addc_u32 s69, s1, 0
	s_add_u32 s70, s0, 0x3d000c8
	s_addc_u32 s71, s1, 0
	s_add_u32 s72, s0, 0x3d000cc
	s_addc_u32 s73, s1, 0
	s_add_u32 s78, s0, 0x3d000d0
	s_addc_u32 s79, s1, 0
	s_add_u32 s80, s0, 0x3d000d4
	s_addc_u32 s81, s1, 0
	s_add_u32 s82, s0, 0x3d000d8
	s_addc_u32 s83, s1, 0
	s_add_u32 s90, s0, 0x3d000dc
	s_addc_u32 s91, s1, 0
	v_readlane_b32 s0, v237, 31
	v_readlane_b32 s1, v237, 32
	s_waitcnt vmcnt(5)
	v_add_u32_e32 v1, 0x7f, v2
	v_add_u32_e32 v2, 0x7f, v3
	v_add_u32_e32 v3, 0x7f, v4
	v_ashrrev_i32_e32 v1, 7, v1
	v_ashrrev_i32_e32 v2, 7, v2
	v_add_u32_e32 v4, 0x7f, v5
	v_ashrrev_i32_e32 v3, 7, v3
	v_add_u32_e32 v1, v2, v1
	s_waitcnt vmcnt(4)
	v_add_u32_e32 v5, 0x7f, v6
	v_add_u32_e32 v6, 0x7f, v7
	v_add_u32_e32 v7, 0x7f, v8
	v_add_u32_e32 v8, 0x7f, v9
	v_ashrrev_i32_e32 v4, 7, v4
	s_waitcnt vmcnt(3)
	v_add_u32_e32 v9, 0x7f, v10
	v_add_u32_e32 v1, v1, v3
	v_add_u32_e32 v10, 0x7f, v11
	v_ashrrev_i32_e32 v2, 7, v9
	v_add_u32_e32 v1, v1, v4
	v_add_u32_e32 v11, 0x7f, v12
	v_ashrrev_i32_e32 v9, 7, v10
	v_add_u32_e32 v1, v1, v2
	v_add_u32_e32 v12, 0x7f, v13
	v_ashrrev_i32_e32 v10, 7, v11
	v_add_u32_e32 v1, v1, v9
	s_waitcnt vmcnt(2)
	v_add_u32_e32 v13, 0x7f, v14
	v_ashrrev_i32_e32 v11, 7, v12
	v_add_u32_e32 v1, v1, v10
	v_add_u32_e32 v14, 0x7f, v15
	v_ashrrev_i32_e32 v12, 7, v13
	v_add_u32_e32 v1, v1, v11
	v_add_u32_e32 v15, 0x7f, v16
	v_ashrrev_i32_e32 v13, 7, v14
	v_add_u32_e32 v1, v1, v12
	v_add_u32_e32 v16, 0x7f, v17
	v_ashrrev_i32_e32 v14, 7, v15
	v_add_u32_e32 v1, v1, v13
	s_waitcnt vmcnt(1)
	v_add_u32_e32 v17, 0x7f, v18
	v_ashrrev_i32_e32 v15, 7, v16
	v_add_u32_e32 v1, v1, v14
	v_add_u32_e32 v18, 0x7f, v19
	v_ashrrev_i32_e32 v17, 7, v17
	v_add_u32_e32 v1, v1, v15
	v_add_u32_e32 v19, 0x7f, v20
	v_ashrrev_i32_e32 v16, 7, v18
	v_add_u32_e32 v1, v1, v17
	v_add_u32_e32 v20, 0x7f, v21
	v_ashrrev_i32_e32 v19, 7, v19
	v_add_u32_e32 v1, v1, v16
	v_ashrrev_i32_e32 v18, 7, v20
	v_add_u32_e32 v1, v1, v19
	v_ashrrev_i32_e32 v5, 7, v5
	v_add_u32_e32 v1, v1, v18
	v_ashrrev_i32_e32 v6, 7, v6
	v_add_u32_e32 v1, v1, v5
	v_ashrrev_i32_e32 v7, 7, v7
	v_add_u32_e32 v1, v1, v6
	v_ashrrev_i32_e32 v8, 7, v8
	s_waitcnt vmcnt(0)
	v_add_u32_e32 v2, 0x7f, v22
	v_add_u32_e32 v1, v1, v7
	v_add_u32_e32 v3, 0x7f, v23
	v_ashrrev_i32_e32 v2, 7, v2
	v_add_u32_e32 v1, v1, v8
	v_add_u32_e32 v4, 0x7f, v24
	v_ashrrev_i32_e32 v3, 7, v3
	v_add_u32_e32 v1, v1, v2
	v_add_u32_e32 v9, 0x7f, v25
	v_ashrrev_i32_e32 v4, 7, v4
	v_add_u32_e32 v1, v1, v3
	v_ashrrev_i32_e32 v9, 7, v9
	v_add_u32_e32 v1, v1, v4
	v_add_u32_e32 v1, v1, v9
	v_lshlrev_b32_e32 v129, 3, v1
	v_cmp_ge_i32_e32 vcc, s0, v129
	v_mov_b32_e32 v12, v128
	s_cbranch_vccnz .LBB0_1858
	global_load_dword v238, v0, s[2:3] offset:52
	global_load_dword v239, v0, s[2:3] offset:56
	global_load_dword v240, v0, s[2:3] offset:60
	global_load_dword v241, v0, s[2:3] offset:64
	global_load_dword v242, v0, s[2:3] offset:68
	global_load_dword v243, v0, s[2:3] offset:72
	global_load_dword v244, v0, s[2:3] offset:76
	global_load_dword v245, v0, s[2:3] offset:80
	global_load_dword v246, v0, s[2:3] offset:84
	global_load_dword v247, v0, s[2:3] offset:88
	global_load_dword v248, v0, s[2:3] offset:92
	global_load_dword v13, v0, s[2:3] offset:48
	global_load_dwordx4 v[4:7], v0, s[2:3] offset:16
	global_load_dwordx4 v[8:11], v0, s[2:3]
	s_nop 0
	global_load_dwordx4 v[0:3], v0, s[2:3] offset:32
	v_readlane_b32 s0, v237, 31
	s_ashr_i32 s16, s0, 3
	v_readlane_b32 s1, v237, 32
	s_cmp_gt_i32 s16, -1
	s_cselect_b64 s[0:1], -1, 0
	s_lshl_b32 s6, s16, 7
	s_waitcnt vmcnt(3)
	v_add_u32_e32 v37, 0x7f, v13
	s_waitcnt vmcnt(2)
	v_add_u32_e32 v21, 0x7f, v4
	s_waitcnt vmcnt(1)
	v_add_u32_e32 v14, 0x7f, v8
	v_add_u32_e32 v15, 0x7f, v9
	v_ashrrev_i32_e32 v14, 7, v14
	v_ashrrev_i32_e32 v15, 7, v15
	v_add_u32_e32 v16, 0x7f, v10
	v_add_u32_e32 v15, v15, v14
	v_ashrrev_i32_e32 v16, 7, v16
	v_add_u32_e32 v19, 0x7f, v11
	v_add_u32_e32 v18, v16, v15
	v_ashrrev_i32_e32 v19, 7, v19
	v_add_u32_e32 v20, v19, v18
	v_ashrrev_i32_e32 v21, 7, v21
	v_add_u32_e32 v23, 0x7f, v5
	v_add_u32_e32 v22, v21, v20
	v_ashrrev_i32_e32 v23, 7, v23
	v_add_u32_e32 v25, 0x7f, v6
	v_add_u32_e32 v24, v23, v22
	v_ashrrev_i32_e32 v25, 7, v25
	v_add_u32_e32 v27, 0x7f, v7
	v_add_u32_e32 v26, v25, v24
	v_ashrrev_i32_e32 v27, 7, v27
	s_waitcnt vmcnt(0)
	v_add_u32_e32 v29, 0x7f, v0
	v_add_u32_e32 v28, v27, v26
	v_ashrrev_i32_e32 v29, 7, v29
	v_add_u32_e32 v17, v9, v8
	v_add_u32_e32 v31, v29, v28
	v_add_u32_e32 v29, 0x7f, v1
	v_add_u32_e32 v16, v10, v17
	v_ashrrev_i32_e32 v29, 7, v29
	v_add_u32_e32 v19, v11, v16
	v_add_u32_e32 v33, v29, v31
	v_add_u32_e32 v29, 0x7f, v2
	v_add_u32_e32 v21, v4, v19
	v_ashrrev_i32_e32 v29, 7, v29
	v_add_u32_e32 v23, v5, v21
	v_add_u32_e32 v35, v29, v33
	v_add_u32_e32 v29, 0x7f, v3
	v_add_u32_e32 v25, v6, v23
	v_ashrrev_i32_e32 v29, 7, v29
	v_cmp_lt_i32_e32 vcc, s16, v14
	v_add_u32_e32 v27, v7, v25
	v_add_u32_e32 v36, v29, v35
	v_ashrrev_i32_e32 v37, 7, v37
	s_and_b64 s[0:1], s[0:1], vcc
	v_add_u32_e32 v30, v0, v27
	v_add_u32_e32 v37, v37, v36
	s_and_b64 s[4:5], s[0:1], exec
	v_add_u32_e32 v32, v1, v30
	v_cmp_ge_i32_e32 vcc, s16, v36
	v_cmp_lt_i32_e64 s[52:53], s16, v37
	s_cselect_b32 s17, s6, 0
	v_add_u32_e32 v34, v2, v32
	s_and_b64 s[52:53], vcc, s[52:53]
	v_cmp_ge_i32_e64 s[4:5], s16, v14
	v_cmp_lt_i32_e64 s[6:7], s16, v15
	v_cmp_ge_i32_e64 s[8:9], s16, v15
	v_cmp_lt_i32_e64 s[10:11], s16, v18
	v_cmp_ge_i32_e64 s[12:13], s16, v18
	v_cmp_lt_i32_e64 s[14:15], s16, v20
	v_cmp_ge_i32_e64 s[18:19], s16, v20
	v_cmp_lt_i32_e64 s[20:21], s16, v22
	v_cmp_ge_i32_e64 s[22:23], s16, v22
	v_cmp_lt_i32_e64 s[24:25], s16, v24
	v_cmp_ge_i32_e64 s[26:27], s16, v24
	v_cmp_lt_i32_e64 s[28:29], s16, v26
	v_cmp_ge_i32_e64 s[30:31], s16, v26
	v_cmp_lt_i32_e64 s[34:35], s16, v28
	v_cmp_ge_i32_e64 s[36:37], s16, v28
	v_cmp_lt_i32_e64 s[38:39], s16, v31
	v_cmp_ge_i32_e64 s[40:41], s16, v31
	v_cmp_lt_i32_e64 s[42:43], s16, v33
	v_cmp_ge_i32_e64 s[44:45], s16, v33
	v_cmp_lt_i32_e64 s[46:47], s16, v35
	v_cmp_ge_i32_e64 s[48:49], s16, v35
	v_cmp_lt_i32_e64 s[50:51], s16, v36
	v_add_u32_e32 v29, v3, v34
	s_andn2_b64 vcc, exec, s[52:53]
	s_cbranch_vccnz .LBB0_1773
	v_sub_u32_e32 v0, s16, v36
	v_lshlrev_b32_e32 v140, 7, v0
	v_mov_b32_e32 v130, 12
	v_mov_b32_e32 v141, v13
	v_mov_b32_e32 v142, v29
	s_branch .LBB0_1774

.LBB0_1774:
	v_mov_b32_e32 v0, 0
	v_mov_b32_e32 v3, v238
	v_cmp_ge_i32_e32 vcc, s16, v37
	v_add_u32_e32 v4, v13, v29
	v_add_u32_e32 v1, 0x7f, v3
	v_ashrrev_i32_e32 v1, 7, v1
	v_add_u32_e32 v1, v1, v37
	v_cmp_lt_i32_e64 s[0:1], s16, v1
	s_and_b64 s[0:1], vcc, s[0:1]
	s_andn2_b64 vcc, exec, s[0:1]
	s_cbranch_vccnz .LBB0_1776
	v_sub_u32_e32 v2, s16, v37
	v_lshlrev_b32_e32 v140, 7, v2
	v_mov_b32_e32 v130, 13
	v_mov_b32_e32 v141, v3
	v_mov_b32_e32 v142, v4
.LBB0_1776:
	v_mov_b32_e32 v2, v239
	v_cmp_ge_i32_e32 vcc, s16, v1
	v_add_u32_e32 v5, v3, v4
	v_add_u32_e32 v0, 0x7f, v2
	v_ashrrev_i32_e32 v0, 7, v0
	v_add_u32_e32 v0, v0, v1
	v_cmp_lt_i32_e64 s[0:1], s16, v0
	s_and_b64 s[0:1], vcc, s[0:1]
	s_andn2_b64 vcc, exec, s[0:1]
	s_cbranch_vccnz .LBB0_1778
	v_sub_u32_e32 v1, s16, v1
	v_lshlrev_b32_e32 v140, 7, v1
	v_mov_b32_e32 v130, 14
	v_mov_b32_e32 v141, v2
	v_mov_b32_e32 v142, v5
.LBB0_1778:
	v_mov_b32_e32 v4, 0
	v_mov_b32_e32 v3, v240
	v_cmp_ge_i32_e32 vcc, s16, v0
	v_add_u32_e32 v5, v2, v5
	v_add_u32_e32 v1, 0x7f, v3
	v_ashrrev_i32_e32 v1, 7, v1
	v_add_u32_e32 v1, v1, v0
	v_cmp_lt_i32_e64 s[0:1], s16, v1
	s_and_b64 s[0:1], vcc, s[0:1]
	s_andn2_b64 vcc, exec, s[0:1]
	s_cbranch_vccnz .LBB0_1780
	v_sub_u32_e32 v0, s16, v0
	v_lshlrev_b32_e32 v140, 7, v0
	v_mov_b32_e32 v130, 15
	v_mov_b32_e32 v141, v3
	v_mov_b32_e32 v142, v5
.LBB0_1780:
	v_mov_b32_e32 v2, v241
	v_cmp_ge_i32_e32 vcc, s16, v1
	v_add_u32_e32 v5, v3, v5
	v_add_u32_e32 v0, 0x7f, v2
	v_ashrrev_i32_e32 v0, 7, v0
	v_add_u32_e32 v0, v0, v1
	v_cmp_lt_i32_e64 s[0:1], s16, v0
	s_and_b64 s[0:1], vcc, s[0:1]
	s_andn2_b64 vcc, exec, s[0:1]
	s_cbranch_vccnz .LBB0_1782
	v_sub_u32_e32 v1, s16, v1
	v_lshlrev_b32_e32 v140, 7, v1
	v_mov_b32_e32 v130, 16
	v_mov_b32_e32 v141, v2
	v_mov_b32_e32 v142, v5
.LBB0_1782:
	v_mov_b32_e32 v4, 0
	v_mov_b32_e32 v3, v242
	v_cmp_ge_i32_e32 vcc, s16, v0
	v_add_u32_e32 v5, v2, v5
	v_add_u32_e32 v1, 0x7f, v3
	v_ashrrev_i32_e32 v1, 7, v1
	v_add_u32_e32 v1, v1, v0
	v_cmp_lt_i32_e64 s[0:1], s16, v1
	s_and_b64 s[0:1], vcc, s[0:1]
	s_andn2_b64 vcc, exec, s[0:1]
	s_cbranch_vccnz .LBB0_1784
	v_sub_u32_e32 v0, s16, v0
	v_lshlrev_b32_e32 v140, 7, v0
	v_mov_b32_e32 v130, 17
	v_mov_b32_e32 v141, v3
	v_mov_b32_e32 v142, v5
.LBB0_1784:
	v_mov_b32_e32 v2, v243
	v_cmp_ge_i32_e32 vcc, s16, v1
	v_add_u32_e32 v5, v3, v5
	v_add_u32_e32 v0, 0x7f, v2
	v_ashrrev_i32_e32 v0, 7, v0
	v_add_u32_e32 v0, v0, v1
	v_cmp_lt_i32_e64 s[0:1], s16, v0
	s_and_b64 s[0:1], vcc, s[0:1]
	s_andn2_b64 vcc, exec, s[0:1]
	s_cbranch_vccnz .LBB0_1786
	v_sub_u32_e32 v1, s16, v1
	v_lshlrev_b32_e32 v140, 7, v1
	v_mov_b32_e32 v130, 18
	v_mov_b32_e32 v141, v2
	v_mov_b32_e32 v142, v5
.LBB0_1786:
	v_mov_b32_e32 v3, 0
	v_mov_b32_e32 v4, v244
	v_cmp_ge_i32_e32 vcc, s16, v0
	v_add_u32_e32 v2, v2, v5
	v_add_u32_e32 v1, 0x7f, v4
	v_ashrrev_i32_e32 v1, 7, v1
	v_add_u32_e32 v1, v1, v0
	v_cmp_lt_i32_e64 s[0:1], s16, v1
	s_and_b64 s[0:1], vcc, s[0:1]
	s_andn2_b64 vcc, exec, s[0:1]
	s_cbranch_vccnz .LBB0_1788
	v_sub_u32_e32 v0, s16, v0
	v_lshlrev_b32_e32 v140, 7, v0
	v_mov_b32_e32 v130, 19
	v_mov_b32_e32 v141, v4
	v_mov_b32_e32 v142, v2
.LBB0_1788:
	v_mov_b32_e32 v3, v245
	v_cmp_ge_i32_e32 vcc, s16, v1
	v_add_u32_e32 v5, v4, v2
	v_add_u32_e32 v0, 0x7f, v3
	v_ashrrev_i32_e32 v0, 7, v0
	v_add_u32_e32 v0, v0, v1
	v_cmp_lt_i32_e64 s[0:1], s16, v0
	s_and_b64 s[0:1], vcc, s[0:1]
	s_andn2_b64 vcc, exec, s[0:1]
	s_cbranch_vccnz .LBB0_1790
	v_sub_u32_e32 v1, s16, v1
	v_lshlrev_b32_e32 v140, 7, v1
	v_mov_b32_e32 v130, 20
	v_mov_b32_e32 v141, v3
	v_mov_b32_e32 v142, v5
.LBB0_1790:
	v_mov_b32_e32 v1, 0
	v_mov_b32_e32 v4, v246
	v_cmp_ge_i32_e32 vcc, s16, v0
	v_add_u32_e32 v3, v3, v5
	v_add_u32_e32 v2, 0x7f, v4
	v_ashrrev_i32_e32 v2, 7, v2
	v_add_u32_e32 v2, v2, v0
	v_cmp_lt_i32_e64 s[0:1], s16, v2
	s_and_b64 s[0:1], vcc, s[0:1]
	s_andn2_b64 vcc, exec, s[0:1]
	s_cbranch_vccnz .LBB0_1792
	v_sub_u32_e32 v0, s16, v0
	v_lshlrev_b32_e32 v140, 7, v0
	v_mov_b32_e32 v130, 21
	v_mov_b32_e32 v141, v4
	v_mov_b32_e32 v142, v3
.LBB0_1792:
	v_mov_b32_e32 v0, v247
	v_cmp_ge_i32_e32 vcc, s16, v2
	v_add_u32_e32 v3, v4, v3
	v_add_u32_e32 v1, 0x7f, v0
	v_ashrrev_i32_e32 v1, 7, v1
	v_add_u32_e32 v1, v1, v2
	v_cmp_lt_i32_e64 s[0:1], s16, v1
	s_and_b64 s[0:1], vcc, s[0:1]
	s_andn2_b64 vcc, exec, s[0:1]
	s_cbranch_vccnz .LBB0_1794
	v_sub_u32_e32 v2, s16, v2
	v_lshlrev_b32_e32 v140, 7, v2
	v_mov_b32_e32 v130, 22
	v_mov_b32_e32 v141, v0
	v_mov_b32_e32 v142, v3
.LBB0_1794:
	v_mov_b32_e32 v131, 0
	v_mov_b32_e32 v2, v248
	v_cmp_ge_i32_e32 vcc, s16, v1
	s_mov_b32 s84, s96
	v_add_u32_e32 v4, 0x7f, v2
	v_ashrrev_i32_e32 v4, 7, v4
	v_add_u32_e32 v4, v4, v1
	v_cmp_lt_i32_e64 s[0:1], s16, v4
	s_and_b64 s[0:1], vcc, s[0:1]
	s_andn2_b64 vcc, exec, s[0:1]
	s_cbranch_vccnz .LBB0_1796
	v_add_u32_e32 v142, v0, v3
	v_sub_u32_e32 v0, s16, v1
	v_lshlrev_b32_e32 v140, 7, v0
	v_mov_b32_e32 v130, 23
	v_mov_b32_e32 v141, v2

.LBB0_1798:
	global_load_dword v238, v131, s[2:3] offset:52
	global_load_dword v239, v131, s[2:3] offset:56
	global_load_dword v240, v131, s[2:3] offset:60
	global_load_dword v241, v131, s[2:3] offset:64
	global_load_dword v242, v131, s[2:3] offset:68
	global_load_dword v243, v131, s[2:3] offset:72
	global_load_dword v244, v131, s[2:3] offset:76
	global_load_dword v245, v131, s[2:3] offset:80
	global_load_dword v246, v131, s[2:3] offset:84
	global_load_dword v247, v131, s[2:3] offset:88
	global_load_dword v248, v131, s[2:3] offset:92
	global_load_dwordx4 v[72:75], v131, s[2:3]
	global_load_dwordx4 v[68:71], v131, s[2:3] offset:16
	global_load_dwordx4 v[64:67], v131, s[2:3] offset:32
	global_load_dword v76, v131, s[2:3] offset:48
	v_readlane_b32 s4, v237, 56
	v_readlane_b32 s6, v237, 58
	v_readlane_b32 s7, v237, 59
	s_add_i32 s17, s60, s6
	v_cmp_lt_i32_e64 s[6:7], s17, v129
	s_and_b64 s[0:1], s[6:7], exec
	s_cselect_b32 s61, s17, s60
	s_ashr_i32 s94, s61, 3
	s_cmp_gt_i32 s94, -1
	s_cselect_b64 s[0:1], -1, 0
	s_lshl_b32 s8, s94, 7
	v_readlane_b32 s5, v237, 57
	v_cmp_ge_i32_e64 s[4:5], s17, v129
	s_waitcnt vmcnt(3)
	v_add_u32_e32 v78, 0x7f, v72
	v_add_u32_e32 v79, 0x7f, v73
	v_add_u32_e32 v80, 0x7f, v74
	v_ashrrev_i32_e32 v96, 7, v78
	v_ashrrev_i32_e32 v78, 7, v79
	v_add_u32_e32 v81, 0x7f, v75
	v_ashrrev_i32_e32 v79, 7, v80
	v_add_u32_e32 v99, v78, v96
	s_waitcnt vmcnt(2)
	v_add_u32_e32 v82, 0x7f, v68
	v_ashrrev_i32_e32 v80, 7, v81
	v_add_u32_e32 v98, v79, v99
	v_add_u32_e32 v83, 0x7f, v69
	v_ashrrev_i32_e32 v81, 7, v82
	v_add_u32_e32 v97, v80, v98
	v_add_u32_e32 v84, 0x7f, v70
	v_ashrrev_i32_e32 v82, 7, v83
	v_add_u32_e32 v95, v81, v97
	v_add_u32_e32 v77, v73, v72
	v_add_u32_e32 v85, 0x7f, v71
	v_ashrrev_i32_e32 v84, 7, v84
	v_add_u32_e32 v94, v82, v95
	s_waitcnt vmcnt(1)
	v_add_u32_e32 v86, 0x7f, v64
	s_waitcnt vmcnt(0)
	v_add_u32_e32 v91, 0x7f, v76
	v_add_u32_e32 v88, v74, v77
	v_ashrrev_i32_e32 v92, 7, v85
	v_add_u32_e32 v93, v84, v94
	v_add_u32_e32 v87, 0x7f, v65
	v_add_u32_e32 v89, 0x7f, v66
	v_add_u32_e32 v90, 0x7f, v67
	v_ashrrev_i32_e32 v86, 7, v86
	v_ashrrev_i32_e32 v103, 7, v91
	v_add_u32_e32 v91, v75, v88
	v_add_u32_e32 v92, v92, v93
	v_ashrrev_i32_e32 v100, 7, v87
	v_ashrrev_i32_e32 v101, 7, v89
	v_ashrrev_i32_e32 v102, 7, v90
	v_add_u32_e32 v90, v68, v91
	v_add_u32_e32 v89, v86, v92
	v_add_u32_e32 v87, v69, v90
	v_add_u32_e32 v86, v100, v89
	v_add_u32_e32 v85, v70, v87
	v_add_u32_e32 v84, v101, v86
	v_cmp_lt_i32_e32 vcc, s94, v96
	v_add_u32_e32 v83, v71, v85
	v_add_u32_e32 v100, v102, v84
	s_and_b64 s[54:55], s[0:1], vcc
	v_add_u32_e32 v82, v64, v83
	v_add_u32_e32 v78, v103, v100
	s_and_b64 s[0:1], s[54:55], exec
	v_add_u32_e32 v81, v65, v82
	v_cmp_ge_i32_e32 vcc, s94, v100
	v_cmp_lt_i32_e64 s[56:57], s94, v78
	s_cselect_b32 s74, s8, 0
	v_add_u32_e32 v80, v66, v81
	s_and_b64 s[56:57], vcc, s[56:57]
	v_cmp_ge_i32_e64 s[48:49], s94, v96
	v_cmp_lt_i32_e64 s[52:53], s94, v99
	v_cmp_ge_i32_e64 s[44:45], s94, v99
	v_cmp_lt_i32_e64 s[50:51], s94, v98
	v_cmp_ge_i32_e64 s[40:41], s94, v98
	v_cmp_lt_i32_e64 s[46:47], s94, v97
	v_cmp_ge_i32_e64 s[38:39], s94, v97
	v_cmp_lt_i32_e64 s[42:43], s94, v95
	v_cmp_ge_i32_e64 s[34:35], s94, v95
	v_cmp_lt_i32_e64 s[36:37], s94, v94
	v_cmp_ge_i32_e64 s[28:29], s94, v94
	v_cmp_lt_i32_e64 s[30:31], s94, v93
	v_cmp_ge_i32_e64 s[24:25], s94, v93
	v_cmp_lt_i32_e64 s[26:27], s94, v92
	v_cmp_ge_i32_e64 s[20:21], s94, v92
	v_cmp_lt_i32_e64 s[22:23], s94, v89
	v_cmp_ge_i32_e64 s[14:15], s94, v89
	v_cmp_lt_i32_e64 s[18:19], s94, v86
	v_cmp_ge_i32_e64 s[10:11], s94, v86
	v_cmp_lt_i32_e64 s[12:13], s94, v84
	v_cmp_ge_i32_e64 s[0:1], s94, v84
	v_cmp_lt_i32_e64 s[8:9], s94, v100
	s_andn2_b64 vcc, exec, s[56:57]
	v_add_u32_e32 v79, v67, v80
	s_cbranch_vccnz .LBB0_1800
	v_sub_u32_e32 v64, s94, v100
	v_lshlrev_b32_e32 v149, 7, v64
	v_mov_b32_e32 v134, 12
	v_mov_b32_e32 v150, v76
	v_mov_b32_e32 v151, v79
	s_branch .LBB0_1801

.LBB0_1801:
	v_mov_b32_e32 v66, v238
	v_cmp_ge_i32_e32 vcc, s94, v78
	v_add_u32_e32 v68, v76, v79
	v_add_u32_e32 v64, 0x7f, v66
	v_ashrrev_i32_e32 v64, 7, v64
	v_add_u32_e32 v64, v64, v78
	v_cmp_lt_i32_e64 s[0:1], s94, v64
	s_and_b64 s[0:1], vcc, s[0:1]
	s_andn2_b64 vcc, exec, s[0:1]
	s_cbranch_vccnz .LBB0_1803
	v_sub_u32_e32 v65, s94, v78
	v_lshlrev_b32_e32 v149, 7, v65
	v_mov_b32_e32 v134, 13
	v_mov_b32_e32 v150, v66
	v_mov_b32_e32 v151, v68
.LBB0_1803:
	v_mov_b32_e32 v67, v239
	v_cmp_ge_i32_e32 vcc, s94, v64
	v_add_u32_e32 v66, v66, v68
	v_add_u32_e32 v65, 0x7f, v67
	v_ashrrev_i32_e32 v65, 7, v65
	v_add_u32_e32 v65, v65, v64
	v_cmp_lt_i32_e64 s[0:1], s94, v65
	s_and_b64 s[0:1], vcc, s[0:1]
	s_andn2_b64 vcc, exec, s[0:1]
	s_cbranch_vccnz .LBB0_1805
	v_sub_u32_e32 v64, s94, v64
	v_lshlrev_b32_e32 v149, 7, v64
	v_mov_b32_e32 v134, 14
	v_mov_b32_e32 v150, v67
	v_mov_b32_e32 v151, v66
.LBB0_1805:
	v_mov_b32_e32 v68, v240
	v_cmp_ge_i32_e32 vcc, s94, v65
	v_add_u32_e32 v69, v67, v66
	v_add_u32_e32 v64, 0x7f, v68
	v_ashrrev_i32_e32 v64, 7, v64
	v_add_u32_e32 v64, v64, v65
	v_cmp_lt_i32_e64 s[0:1], s94, v64
	s_and_b64 s[0:1], vcc, s[0:1]
	s_andn2_b64 vcc, exec, s[0:1]
	s_cbranch_vccnz .LBB0_1807
	v_sub_u32_e32 v65, s94, v65
	v_lshlrev_b32_e32 v149, 7, v65
	v_mov_b32_e32 v134, 15
	v_mov_b32_e32 v150, v68
	v_mov_b32_e32 v151, v69
.LBB0_1807:
	v_mov_b32_e32 v67, v241
	v_cmp_ge_i32_e32 vcc, s94, v64
	v_add_u32_e32 v69, v68, v69
	v_add_u32_e32 v65, 0x7f, v67
	v_ashrrev_i32_e32 v65, 7, v65
	v_add_u32_e32 v66, v65, v64
	v_cmp_lt_i32_e64 s[0:1], s94, v66
	s_and_b64 s[0:1], vcc, s[0:1]
	s_andn2_b64 vcc, exec, s[0:1]
	s_cbranch_vccnz .LBB0_1809
	v_sub_u32_e32 v64, s94, v64
	v_lshlrev_b32_e32 v149, 7, v64
	v_mov_b32_e32 v134, 16
	v_mov_b32_e32 v150, v67
	v_mov_b32_e32 v151, v69
.LBB0_1809:
	v_mov_b32_e32 v68, v242
	v_cmp_ge_i32_e32 vcc, s94, v66
	v_add_u32_e32 v67, v67, v69
	v_add_u32_e32 v64, 0x7f, v68
	v_ashrrev_i32_e32 v64, 7, v64
	v_add_u32_e32 v65, v64, v66
	v_cmp_lt_i32_e64 s[0:1], s94, v65
	s_and_b64 s[0:1], vcc, s[0:1]
	s_andn2_b64 vcc, exec, s[0:1]
	s_cbranch_vccnz .LBB0_1811
	v_sub_u32_e32 v64, s94, v66
	v_lshlrev_b32_e32 v149, 7, v64
	v_mov_b32_e32 v134, 17
	v_mov_b32_e32 v150, v68
	v_mov_b32_e32 v151, v67
.LBB0_1811:
	v_mov_b32_e32 v66, v243
	v_cmp_ge_i32_e32 vcc, s94, v65
	v_add_u32_e32 v68, v68, v67
	v_add_u32_e32 v64, 0x7f, v66
	v_ashrrev_i32_e32 v64, 7, v64
	v_add_u32_e32 v64, v64, v65
	v_cmp_lt_i32_e64 s[0:1], s94, v64
	s_and_b64 s[0:1], vcc, s[0:1]
	s_andn2_b64 vcc, exec, s[0:1]
	s_cbranch_vccnz .LBB0_1813
	v_sub_u32_e32 v65, s94, v65
	v_lshlrev_b32_e32 v149, 7, v65
	v_mov_b32_e32 v134, 18
	v_mov_b32_e32 v150, v66
	v_mov_b32_e32 v151, v68
.LBB0_1813:
	v_mov_b32_e32 v67, v244
	v_cmp_ge_i32_e32 vcc, s94, v64
	v_add_u32_e32 v68, v66, v68
	v_add_u32_e32 v65, 0x7f, v67
	v_ashrrev_i32_e32 v65, 7, v65
	v_add_u32_e32 v65, v65, v64
	v_cmp_lt_i32_e64 s[0:1], s94, v65
	s_and_b64 s[0:1], vcc, s[0:1]
	s_andn2_b64 vcc, exec, s[0:1]
	s_cbranch_vccnz .LBB0_1815
	v_sub_u32_e32 v64, s94, v64
	v_lshlrev_b32_e32 v149, 7, v64
	v_mov_b32_e32 v134, 19
	v_mov_b32_e32 v150, v67
	v_mov_b32_e32 v151, v68
.LBB0_1815:
	v_mov_b32_e32 v66, v245
	v_cmp_ge_i32_e32 vcc, s94, v65
	v_add_u32_e32 v68, v67, v68
	v_add_u32_e32 v64, 0x7f, v66
	v_ashrrev_i32_e32 v64, 7, v64
	v_add_u32_e32 v64, v64, v65
	v_cmp_lt_i32_e64 s[0:1], s94, v64
	s_and_b64 s[0:1], vcc, s[0:1]
	s_andn2_b64 vcc, exec, s[0:1]
	s_cbranch_vccnz .LBB0_1817
	v_sub_u32_e32 v65, s94, v65
	v_lshlrev_b32_e32 v149, 7, v65
	v_mov_b32_e32 v134, 20
	v_mov_b32_e32 v150, v66
	v_mov_b32_e32 v151, v68
.LBB0_1817:
	v_mov_b32_e32 v67, v246
	v_cmp_ge_i32_e32 vcc, s94, v64
	v_add_u32_e32 v68, v66, v68
	v_add_u32_e32 v65, 0x7f, v67
	v_ashrrev_i32_e32 v65, 7, v65
	v_add_u32_e32 v65, v65, v64
	v_cmp_lt_i32_e64 s[0:1], s94, v65
	s_and_b64 s[0:1], vcc, s[0:1]
	s_andn2_b64 vcc, exec, s[0:1]
	s_cbranch_vccnz .LBB0_1819
	v_sub_u32_e32 v64, s94, v64
	v_lshlrev_b32_e32 v149, 7, v64
	v_mov_b32_e32 v134, 21
	v_mov_b32_e32 v150, v67
	v_mov_b32_e32 v151, v68
.LBB0_1819:
	v_mov_b32_e32 v64, v247
	v_cmp_ge_i32_e32 vcc, s94, v65
	v_add_u32_e32 v67, v67, v68
	v_add_u32_e32 v66, 0x7f, v64
	v_ashrrev_i32_e32 v66, 7, v66
	v_add_u32_e32 v66, v66, v65
	v_cmp_lt_i32_e64 s[0:1], s94, v66
	s_and_b64 s[0:1], vcc, s[0:1]
	s_andn2_b64 vcc, exec, s[0:1]
	s_cbranch_vccnz .LBB0_1821
	v_sub_u32_e32 v65, s94, v65
	v_lshlrev_b32_e32 v149, 7, v65
	v_mov_b32_e32 v134, 22
	v_mov_b32_e32 v150, v64
	v_mov_b32_e32 v151, v67
.LBB0_1821:
	v_mov_b32_e32 v65, v248
	v_cmp_ge_i32_e32 vcc, s94, v66
	v_add_u32_e32 v68, 0x7f, v65
	v_ashrrev_i32_e32 v68, 7, v68
	v_add_u32_e32 v68, v68, v66
	v_cmp_lt_i32_e64 s[0:1], s94, v68
	s_and_b64 s[0:1], vcc, s[0:1]
	s_andn2_b64 vcc, exec, s[0:1]
	s_cbranch_vccnz .LBB0_1823
	v_add_u32_e32 v151, v64, v67
	v_sub_u32_e32 v64, s94, v66
	v_lshlrev_b32_e32 v149, 7, v64
	v_mov_b32_e32 v134, 23
	v_mov_b32_e32 v150, v65

.LBB0_1910:
	s_or_b64 exec, exec, s[0:1]
	s_waitcnt vmcnt(7)
	v_mov_b32_e32 v9, 0
	s_waitcnt lgkmcnt(0)
	s_barrier
	global_load_dwordx4 v[0:3], v9, s[2:3]
	global_load_dwordx4 v[4:7], v9, s[2:3] offset:16
	global_load_dwordx4 v[10:13], v9, s[2:3] offset:32
	global_load_dwordx4 v[14:17], v9, s[2:3] offset:48
	global_load_dwordx4 v[18:21], v9, s[66:67]
	global_load_dwordx4 v[22:25], v9, s[66:67] offset:16
	v_readlane_b32 s0, v237, 31
	v_readlane_b32 s1, v237, 32
	s_waitcnt vmcnt(5)
	v_add_u32_e32 v0, 0x7f, v0
	v_add_u32_e32 v1, 0x7f, v1
	v_add_u32_e32 v2, 0x7f, v2
	v_ashrrev_i32_e32 v0, 7, v0
	v_ashrrev_i32_e32 v1, 7, v1
	v_add_u32_e32 v3, 0x7f, v3
	v_ashrrev_i32_e32 v2, 7, v2
	v_add_u32_e32 v0, v1, v0
	s_waitcnt vmcnt(4)
	v_add_u32_e32 v4, 0x7f, v4
	v_ashrrev_i32_e32 v3, 7, v3
	v_add_u32_e32 v0, v0, v2
	v_add_u32_e32 v5, 0x7f, v5
	v_ashrrev_i32_e32 v4, 7, v4
	v_add_u32_e32 v0, v0, v3
	v_add_u32_e32 v6, 0x7f, v6
	v_ashrrev_i32_e32 v5, 7, v5
	v_add_u32_e32 v0, v0, v4
	v_add_u32_e32 v7, 0x7f, v7
	v_ashrrev_i32_e32 v6, 7, v6
	v_add_u32_e32 v0, v0, v5
	s_waitcnt vmcnt(3)
	v_add_u32_e32 v8, 0x7f, v10
	v_ashrrev_i32_e32 v7, 7, v7
	v_add_u32_e32 v0, v0, v6
	v_add_u32_e32 v10, 0x7f, v11
	v_ashrrev_i32_e32 v8, 7, v8
	v_add_u32_e32 v0, v0, v7
	v_add_u32_e32 v11, 0x7f, v12
	v_ashrrev_i32_e32 v10, 7, v10
	v_add_u32_e32 v0, v0, v8
	v_add_u32_e32 v12, 0x7f, v13
	v_ashrrev_i32_e32 v11, 7, v11
	v_add_u32_e32 v0, v0, v10
	s_waitcnt vmcnt(2)
	v_add_u32_e32 v13, 0x7f, v14
	v_ashrrev_i32_e32 v12, 7, v12
	v_add_u32_e32 v0, v0, v11
	v_add_u32_e32 v14, 0x7f, v15
	v_ashrrev_i32_e32 v13, 7, v13
	v_add_u32_e32 v0, v0, v12
	v_add_u32_e32 v15, 0x7f, v16
	v_ashrrev_i32_e32 v14, 7, v14
	v_add_u32_e32 v0, v0, v13
	v_add_u32_e32 v16, 0x7f, v17
	v_ashrrev_i32_e32 v15, 7, v15
	v_add_u32_e32 v0, v0, v14
	s_waitcnt vmcnt(1)
	v_add_u32_e32 v17, 0x7f, v18
	v_ashrrev_i32_e32 v16, 7, v16
	v_add_u32_e32 v0, v0, v15
	v_add_u32_e32 v18, 0x7f, v19
	v_ashrrev_i32_e32 v17, 7, v17
	v_add_u32_e32 v0, v0, v16
	v_add_u32_e32 v19, 0x7f, v20
	v_ashrrev_i32_e32 v18, 7, v18
	v_add_u32_e32 v0, v0, v17
	v_add_u32_e32 v20, 0x7f, v21
	v_ashrrev_i32_e32 v19, 7, v19
	v_add_u32_e32 v0, v0, v18
	s_waitcnt vmcnt(0)
	v_add_u32_e32 v21, 0x7f, v22
	v_ashrrev_i32_e32 v20, 7, v20
	v_add_u32_e32 v0, v0, v19
	v_add_u32_e32 v22, 0x7f, v23
	v_ashrrev_i32_e32 v21, 7, v21
	v_add_u32_e32 v0, v0, v20
	v_add_u32_e32 v23, 0x7f, v24
	v_ashrrev_i32_e32 v22, 7, v22
	v_add_u32_e32 v0, v0, v21
	v_add_u32_e32 v24, 0x7f, v25
	v_ashrrev_i32_e32 v23, 7, v23
	v_add_u32_e32 v0, v0, v22
	v_ashrrev_i32_e32 v24, 7, v24
	v_add_u32_e32 v0, v0, v23
	v_add_u32_e32 v0, v0, v24
	v_lshlrev_b32_e32 v129, 3, v0
	v_cmp_ge_i32_e32 vcc, s0, v129
	v_mov_b32_e32 v8, v128
	s_cbranch_vccnz .LBB0_1997
	global_load_dword v238, v9, s[2:3] offset:52
	global_load_dword v239, v9, s[2:3] offset:56
	global_load_dword v240, v9, s[2:3] offset:60
	global_load_dword v241, v9, s[2:3] offset:64
	global_load_dword v242, v9, s[2:3] offset:68
	global_load_dword v243, v9, s[2:3] offset:72
	global_load_dword v244, v9, s[2:3] offset:76
	global_load_dword v245, v9, s[2:3] offset:80
	global_load_dword v246, v9, s[2:3] offset:84
	global_load_dword v247, v9, s[2:3] offset:88
	global_load_dword v248, v9, s[2:3] offset:92
	global_load_dwordx4 v[4:7], v9, s[2:3] offset:16
	global_load_dwordx4 v[10:13], v9, s[2:3]
	global_load_dwordx4 v[0:3], v9, s[2:3] offset:32
	s_nop 0
	global_load_dword v9, v9, s[2:3] offset:48
	s_ashr_i32 s33, s0, 3
	s_cmp_gt_i32 s33, -1
	s_cselect_b64 s[0:1], -1, 0
	s_lshl_b32 s5, s33, 7
	s_waitcnt vmcnt(3)
	v_readfirstlane_b32 s4, v4
	s_waitcnt vmcnt(2)
	v_readfirstlane_b32 s11, v10
	s_add_i32 s6, s11, 0x7f
	s_ashr_i32 s12, s6, 7
	s_cmp_lt_i32 s33, s12
	s_cselect_b64 s[6:7], -1, 0
	s_and_b64 s[0:1], s[0:1], s[6:7]
	v_readfirstlane_b32 s10, v11
	s_and_b64 s[0:1], s[0:1], exec
	s_cselect_b32 s5, s5, 0
	s_cselect_b32 s13, s11, 0
	s_add_i32 s0, s10, 0x7f
	s_ashr_i32 s6, s0, 7
	s_cmp_ge_i32 s33, s12
	s_cselect_b64 s[0:1], -1, 0
	s_add_i32 s14, s6, s12
	s_cmp_lt_i32 s33, s14
	s_cselect_b64 s[6:7], -1, 0
	s_sub_i32 s12, s33, s12
	s_and_b64 s[16:17], s[0:1], s[6:7]
	s_lshl_b32 s6, s12, 7
	v_readfirstlane_b32 s9, v12
	s_and_b64 s[0:1], s[16:17], exec
	s_cselect_b32 s5, s6, s5
	s_cselect_b32 s12, s11, 0
	s_cselect_b32 s13, s10, s13
	s_add_i32 s0, s9, 0x7f
	s_add_i32 s10, s10, s11
	s_ashr_i32 s6, s0, 7
	s_cmp_ge_i32 s33, s14
	s_cselect_b64 s[0:1], -1, 0
	s_add_i32 s11, s6, s14
	s_cmp_lt_i32 s33, s11
	s_cselect_b64 s[6:7], -1, 0
	s_sub_i32 s14, s33, s14
	s_and_b64 s[34:35], s[0:1], s[6:7]
	s_lshl_b32 s6, s14, 7
	v_readfirstlane_b32 s8, v13
	s_and_b64 s[0:1], s[34:35], exec
	s_cselect_b32 s5, s6, s5
	s_cselect_b32 s13, s9, s13
	s_cselect_b32 s12, s10, s12
	s_add_i32 s0, s8, 0x7f
	s_add_i32 s9, s9, s10
	s_ashr_i32 s6, s0, 7
	s_cmp_ge_i32 s33, s11
	s_cselect_b64 s[0:1], -1, 0
	s_add_i32 s10, s6, s11
	s_cmp_lt_i32 s33, s10
	s_cselect_b64 s[6:7], -1, 0
	s_sub_i32 s11, s33, s11
	s_and_b64 s[36:37], s[0:1], s[6:7]
	s_lshl_b32 s6, s11, 7
	s_and_b64 s[0:1], s[36:37], exec
	s_cselect_b32 s5, s6, s5
	s_cselect_b32 s11, s9, s12
	s_cselect_b32 s12, s8, s13
	s_add_i32 s0, s4, 0x7f
	s_add_i32 s8, s8, s9
	s_ashr_i32 s6, s0, 7
	s_cmp_ge_i32 s33, s10
	v_add_u32_e32 v4, 0x7f, v5
	s_cselect_b64 s[0:1], -1, 0
	s_add_i32 s9, s6, s10
	v_add_u32_e32 v10, 0x7f, v6
	v_ashrrev_i32_e32 v4, 7, v4
	s_cmp_lt_i32 s33, s9
	v_add_u32_e32 v11, 0x7f, v7
	v_ashrrev_i32_e32 v10, 7, v10
	v_add_u32_e32 v18, s9, v4
	s_cselect_b64 s[6:7], -1, 0
	s_sub_i32 s10, s33, s10
	s_waitcnt vmcnt(1)
	v_add_u32_e32 v12, 0x7f, v0
	v_add_u32_e32 v15, 0x7f, v3
	v_ashrrev_i32_e32 v11, 7, v11
	v_add_u32_e32 v16, v10, v18
	s_and_b64 s[38:39], s[0:1], s[6:7]
	s_lshl_b32 s10, s10, 7
	v_add_u32_e32 v13, 0x7f, v1
	v_ashrrev_i32_e32 v12, 7, v12
	v_ashrrev_i32_e32 v23, 7, v15
	v_add_u32_e32 v15, v11, v16
	s_and_b64 s[0:1], s[38:39], exec
	v_add_u32_e32 v14, 0x7f, v2
	v_ashrrev_i32_e32 v17, 7, v13
	v_add_u32_e32 v13, v12, v15
	s_cselect_b32 s18, s10, s5
	s_cselect_b32 s40, s4, s12
	s_cselect_b32 s19, s8, s11
	s_add_i32 s30, s4, s8
	v_ashrrev_i32_e32 v14, 7, v14
	v_add_u32_e32 v12, v17, v13
	s_cmp_ge_i32 s33, s9
	v_add_u32_e32 v22, s30, v5
	v_cmp_lt_i32_e32 vcc, s33, v18
	v_add_u32_e32 v11, v14, v12
	s_cselect_b64 s[10:11], -1, 0
	s_sub_i32 s31, s33, s9
	v_add_u32_e32 v21, v6, v22
	s_waitcnt vmcnt(0)
	v_add_u32_e32 v4, 0x7f, v9
	s_and_b64 s[28:29], s[10:11], vcc
	s_lshl_b32 s31, s31, 7
	v_add_u32_e32 v20, v7, v21
	v_add_u32_e32 v23, v23, v11
	v_ashrrev_i32_e32 v4, 7, v4
	s_and_b64 s[10:11], s[28:29], exec
	v_add_u32_e32 v19, v0, v20
	v_add_u32_e32 v4, v4, v23
	s_cselect_b32 s42, s31, s18
	s_cselect_b32 s41, s30, s19
	v_add_u32_e32 v17, v1, v19
	v_cmp_ge_i32_e32 vcc, s33, v23
	v_cmp_lt_i32_e64 s[30:31], s33, v4
	v_add_u32_e32 v14, v2, v17
	s_and_b64 s[30:31], vcc, s[30:31]
	v_cmp_ge_i32_e64 s[24:25], s33, v18
	v_cmp_lt_i32_e64 s[26:27], s33, v16
	v_cmp_ge_i32_e64 s[14:15], s33, v16
	v_cmp_lt_i32_e64 s[22:23], s33, v15
	v_cmp_ge_i32_e64 s[6:7], s33, v15
	v_cmp_lt_i32_e64 s[20:21], s33, v13
	v_cmp_ge_i32_e64 s[4:5], s33, v13
	v_cmp_lt_i32_e64 s[12:13], s33, v12
	v_cmp_ge_i32_e64 s[0:1], s33, v12
	v_cmp_lt_i32_e64 s[8:9], s33, v11
	v_cmp_ge_i32_e64 s[10:11], s33, v11
	v_cmp_lt_i32_e64 s[18:19], s33, v23
	s_andn2_b64 vcc, exec, s[30:31]
	v_add_u32_e32 v10, v3, v14
	s_cbranch_vccnz .LBB0_1913
	v_sub_u32_e32 v0, s33, v23
	v_lshlrev_b32_e32 v138, 7, v0
	v_mov_b32_e32 v130, 12
	v_mov_b32_e32 v139, v9
	v_mov_b32_e32 v0, v10
	s_branch .LBB0_1914

.LBB0_1914:
	v_mov_b32_e32 v1, 0
	v_mov_b32_e32 v5, v238
	v_cmp_ge_i32_e32 vcc, s33, v4
	v_add_u32_e32 v6, v9, v10
	v_add_u32_e32 v2, 0x7f, v5
	v_ashrrev_i32_e32 v2, 7, v2
	v_add_u32_e32 v2, v2, v4
	v_cmp_lt_i32_e64 s[0:1], s33, v2
	s_and_b64 s[0:1], vcc, s[0:1]
	s_andn2_b64 vcc, exec, s[0:1]
	s_cbranch_vccnz .LBB0_1916
	v_sub_u32_e32 v0, s33, v4
	v_lshlrev_b32_e32 v138, 7, v0
	v_mov_b32_e32 v130, 13
	v_mov_b32_e32 v139, v5
	v_mov_b32_e32 v0, v6
.LBB0_1916:
	v_mov_b32_e32 v3, v239
	v_cmp_ge_i32_e32 vcc, s33, v2
	v_add_u32_e32 v6, v5, v6
	v_add_u32_e32 v1, 0x7f, v3
	v_ashrrev_i32_e32 v1, 7, v1
	v_add_u32_e32 v1, v1, v2
	v_cmp_lt_i32_e64 s[0:1], s33, v1
	s_and_b64 s[0:1], vcc, s[0:1]
	s_andn2_b64 vcc, exec, s[0:1]
	s_cbranch_vccnz .LBB0_1918
	v_sub_u32_e32 v0, s33, v2
	v_lshlrev_b32_e32 v138, 7, v0
	v_mov_b32_e32 v130, 14
	v_mov_b32_e32 v139, v3
	v_mov_b32_e32 v0, v6
.LBB0_1918:
	v_mov_b32_e32 v5, 0
	v_mov_b32_e32 v4, v240
	v_cmp_ge_i32_e32 vcc, s33, v1
	v_add_u32_e32 v6, v3, v6
	v_add_u32_e32 v2, 0x7f, v4
	v_ashrrev_i32_e32 v2, 7, v2
	v_add_u32_e32 v2, v2, v1
	v_cmp_lt_i32_e64 s[0:1], s33, v2
	s_and_b64 s[0:1], vcc, s[0:1]
	s_andn2_b64 vcc, exec, s[0:1]
	s_cbranch_vccnz .LBB0_1920
	v_sub_u32_e32 v0, s33, v1
	v_lshlrev_b32_e32 v138, 7, v0
	v_mov_b32_e32 v130, 15
	v_mov_b32_e32 v139, v4
	v_mov_b32_e32 v0, v6
.LBB0_1920:
	v_mov_b32_e32 v3, v241
	v_cmp_ge_i32_e32 vcc, s33, v2
	v_add_u32_e32 v6, v4, v6
	v_add_u32_e32 v1, 0x7f, v3
	v_ashrrev_i32_e32 v1, 7, v1
	v_add_u32_e32 v1, v1, v2
	v_cmp_lt_i32_e64 s[0:1], s33, v1
	s_and_b64 s[0:1], vcc, s[0:1]
	s_andn2_b64 vcc, exec, s[0:1]
	s_cbranch_vccnz .LBB0_1922
	v_sub_u32_e32 v0, s33, v2
	v_lshlrev_b32_e32 v138, 7, v0
	v_mov_b32_e32 v130, 16
	v_mov_b32_e32 v139, v3
	v_mov_b32_e32 v0, v6
.LBB0_1922:
	v_mov_b32_e32 v5, 0
	v_mov_b32_e32 v4, v242
	v_cmp_ge_i32_e32 vcc, s33, v1
	v_add_u32_e32 v6, v3, v6
	v_add_u32_e32 v2, 0x7f, v4
	v_ashrrev_i32_e32 v2, 7, v2
	v_add_u32_e32 v2, v2, v1
	v_cmp_lt_i32_e64 s[0:1], s33, v2
	s_and_b64 s[0:1], vcc, s[0:1]
	s_andn2_b64 vcc, exec, s[0:1]
	s_cbranch_vccnz .LBB0_1924
	v_sub_u32_e32 v0, s33, v1
	v_lshlrev_b32_e32 v138, 7, v0
	v_mov_b32_e32 v130, 17
	v_mov_b32_e32 v139, v4
	v_mov_b32_e32 v0, v6
.LBB0_1924:
	v_mov_b32_e32 v3, v243
	v_cmp_ge_i32_e32 vcc, s33, v2
	v_add_u32_e32 v6, v4, v6
	v_add_u32_e32 v1, 0x7f, v3
	v_ashrrev_i32_e32 v1, 7, v1
	v_add_u32_e32 v1, v1, v2
	v_cmp_lt_i32_e64 s[0:1], s33, v1
	s_and_b64 s[0:1], vcc, s[0:1]
	s_andn2_b64 vcc, exec, s[0:1]
	s_cbranch_vccnz .LBB0_1926
	v_sub_u32_e32 v0, s33, v2
	v_lshlrev_b32_e32 v138, 7, v0
	v_mov_b32_e32 v130, 18
	v_mov_b32_e32 v139, v3
	v_mov_b32_e32 v0, v6
.LBB0_1926:
	v_mov_b32_e32 v4, 0
	v_mov_b32_e32 v5, v244
	v_cmp_ge_i32_e32 vcc, s33, v1
	v_add_u32_e32 v3, v3, v6
	v_add_u32_e32 v2, 0x7f, v5
	v_ashrrev_i32_e32 v2, 7, v2
	v_add_u32_e32 v2, v2, v1
	v_cmp_lt_i32_e64 s[0:1], s33, v2
	s_and_b64 s[0:1], vcc, s[0:1]
	s_andn2_b64 vcc, exec, s[0:1]
	s_cbranch_vccnz .LBB0_1928
	v_sub_u32_e32 v0, s33, v1
	v_lshlrev_b32_e32 v138, 7, v0
	v_mov_b32_e32 v130, 19
	v_mov_b32_e32 v139, v5
	v_mov_b32_e32 v0, v3
.LBB0_1928:
	v_mov_b32_e32 v4, v245
	v_cmp_ge_i32_e32 vcc, s33, v2
	v_add_u32_e32 v6, v5, v3
	v_add_u32_e32 v1, 0x7f, v4
	v_ashrrev_i32_e32 v1, 7, v1
	v_add_u32_e32 v1, v1, v2
	v_cmp_lt_i32_e64 s[0:1], s33, v1
	s_and_b64 s[0:1], vcc, s[0:1]
	s_andn2_b64 vcc, exec, s[0:1]
	s_cbranch_vccnz .LBB0_1930
	v_sub_u32_e32 v0, s33, v2
	v_lshlrev_b32_e32 v138, 7, v0
	v_mov_b32_e32 v130, 20
	v_mov_b32_e32 v139, v4
	v_mov_b32_e32 v0, v6
.LBB0_1930:
	v_mov_b32_e32 v2, 0
	v_mov_b32_e32 v5, v246
	v_cmp_ge_i32_e32 vcc, s33, v1
	v_add_u32_e32 v4, v4, v6
	v_add_u32_e32 v3, 0x7f, v5
	v_ashrrev_i32_e32 v3, 7, v3
	v_add_u32_e32 v3, v3, v1
	v_cmp_lt_i32_e64 s[0:1], s33, v3
	s_and_b64 s[0:1], vcc, s[0:1]
	s_andn2_b64 vcc, exec, s[0:1]
	s_cbranch_vccnz .LBB0_1932
	v_sub_u32_e32 v0, s33, v1
	v_lshlrev_b32_e32 v138, 7, v0
	v_mov_b32_e32 v130, 21
	v_mov_b32_e32 v139, v5
	v_mov_b32_e32 v0, v4
.LBB0_1932:
	v_mov_b32_e32 v1, v247
	v_cmp_ge_i32_e32 vcc, s33, v3
	v_add_u32_e32 v4, v5, v4
	v_add_u32_e32 v2, 0x7f, v1
	v_ashrrev_i32_e32 v2, 7, v2
	v_add_u32_e32 v2, v2, v3
	v_cmp_lt_i32_e64 s[0:1], s33, v2
	s_and_b64 s[0:1], vcc, s[0:1]
	s_andn2_b64 vcc, exec, s[0:1]
	s_cbranch_vccnz .LBB0_1934
	v_sub_u32_e32 v0, s33, v3
	v_lshlrev_b32_e32 v138, 7, v0
	v_mov_b32_e32 v130, 22
	v_mov_b32_e32 v139, v1
	v_mov_b32_e32 v0, v4
.LBB0_1934:
	v_mov_b32_e32 v133, 0
	v_mov_b32_e32 v3, v248
	v_cmp_ge_i32_e32 vcc, s33, v2
	v_add_u32_e32 v5, 0x7f, v3
	v_ashrrev_i32_e32 v5, 7, v5
	v_add_u32_e32 v5, v5, v2
	v_cmp_lt_i32_e64 s[0:1], s33, v5
	s_and_b64 s[0:1], vcc, s[0:1]
	s_andn2_b64 vcc, exec, s[0:1]
	s_cbranch_vccnz .LBB0_1936
	v_add_u32_e32 v0, v1, v4
	v_sub_u32_e32 v1, s33, v2
	v_lshlrev_b32_e32 v138, 7, v1
	v_mov_b32_e32 v130, 23
	v_mov_b32_e32 v139, v3

.LBB0_1938:
	global_load_dword v238, v133, s[2:3] offset:52
	global_load_dword v239, v133, s[2:3] offset:56
	global_load_dword v240, v133, s[2:3] offset:60
	global_load_dword v241, v133, s[2:3] offset:64
	global_load_dword v242, v133, s[2:3] offset:68
	global_load_dword v243, v133, s[2:3] offset:72
	global_load_dword v244, v133, s[2:3] offset:76
	global_load_dword v245, v133, s[2:3] offset:80
	global_load_dword v246, v133, s[2:3] offset:84
	global_load_dword v247, v133, s[2:3] offset:88
	global_load_dword v248, v133, s[2:3] offset:92
	global_load_dwordx4 v[72:75], v133, s[2:3]
	global_load_dwordx4 v[68:71], v133, s[2:3] offset:16
	global_load_dwordx4 v[64:67], v133, s[2:3] offset:32
	global_load_dword v76, v133, s[2:3] offset:48
	v_readlane_b32 s4, v237, 56
	v_readlane_b32 s6, v237, 58
	v_readlane_b32 s0, v237, 31
	v_readlane_b32 s7, v237, 59
	s_add_i32 s61, s0, s6
	v_readlane_b32 s1, v237, 32
	v_cmp_lt_i32_e64 s[6:7], s61, v129
	s_mov_b32 s8, s0
	s_and_b64 s[0:1], s[6:7], exec
	s_cselect_b32 s92, s61, s8
	s_ashr_i32 s94, s92, 3
	s_cmp_gt_i32 s94, -1
	s_cselect_b64 s[0:1], -1, 0
	s_lshl_b32 s8, s94, 7
	v_readlane_b32 s5, v237, 57
	v_cmp_ge_i32_e64 s[4:5], s61, v129
	s_waitcnt vmcnt(3)
	v_add_u32_e32 v78, 0x7f, v72
	v_add_u32_e32 v79, 0x7f, v73
	v_add_u32_e32 v80, 0x7f, v74
	v_ashrrev_i32_e32 v96, 7, v78
	v_ashrrev_i32_e32 v78, 7, v79
	v_add_u32_e32 v81, 0x7f, v75
	v_ashrrev_i32_e32 v79, 7, v80
	v_add_u32_e32 v99, v78, v96
	s_waitcnt vmcnt(2)
	v_add_u32_e32 v82, 0x7f, v68
	v_ashrrev_i32_e32 v80, 7, v81
	v_add_u32_e32 v98, v79, v99
	v_add_u32_e32 v83, 0x7f, v69
	v_ashrrev_i32_e32 v81, 7, v82
	v_add_u32_e32 v97, v80, v98
	v_add_u32_e32 v84, 0x7f, v70
	v_ashrrev_i32_e32 v82, 7, v83
	v_add_u32_e32 v95, v81, v97
	v_add_u32_e32 v77, v73, v72
	v_add_u32_e32 v85, 0x7f, v71
	v_ashrrev_i32_e32 v84, 7, v84
	v_add_u32_e32 v94, v82, v95
	s_waitcnt vmcnt(1)
	v_add_u32_e32 v86, 0x7f, v64
	s_waitcnt vmcnt(0)
	v_add_u32_e32 v91, 0x7f, v76
	v_add_u32_e32 v88, v74, v77
	v_ashrrev_i32_e32 v92, 7, v85
	v_add_u32_e32 v93, v84, v94
	v_add_u32_e32 v87, 0x7f, v65
	v_add_u32_e32 v89, 0x7f, v66
	v_add_u32_e32 v90, 0x7f, v67
	v_ashrrev_i32_e32 v86, 7, v86
	v_ashrrev_i32_e32 v103, 7, v91
	v_add_u32_e32 v91, v75, v88
	v_add_u32_e32 v92, v92, v93
	v_ashrrev_i32_e32 v100, 7, v87
	v_ashrrev_i32_e32 v101, 7, v89
	v_ashrrev_i32_e32 v102, 7, v90
	v_add_u32_e32 v90, v68, v91
	v_add_u32_e32 v89, v86, v92
	v_add_u32_e32 v87, v69, v90
	v_add_u32_e32 v86, v100, v89
	v_add_u32_e32 v85, v70, v87
	v_add_u32_e32 v84, v101, v86
	v_cmp_lt_i32_e32 vcc, s94, v96
	v_add_u32_e32 v83, v71, v85
	v_add_u32_e32 v100, v102, v84
	s_and_b64 s[54:55], s[0:1], vcc
	v_add_u32_e32 v82, v64, v83
	v_add_u32_e32 v78, v103, v100
	s_and_b64 s[0:1], s[54:55], exec
	v_add_u32_e32 v81, v65, v82
	v_cmp_ge_i32_e32 vcc, s94, v100
	v_cmp_lt_i32_e64 s[56:57], s94, v78
	s_cselect_b32 s74, s8, 0
	v_add_u32_e32 v80, v66, v81
	s_and_b64 s[56:57], vcc, s[56:57]
	v_cmp_ge_i32_e64 s[48:49], s94, v96
	v_cmp_lt_i32_e64 s[52:53], s94, v99
	v_cmp_ge_i32_e64 s[44:45], s94, v99
	v_cmp_lt_i32_e64 s[50:51], s94, v98
	v_cmp_ge_i32_e64 s[42:43], s94, v98
	v_cmp_lt_i32_e64 s[46:47], s94, v97
	v_cmp_ge_i32_e64 s[38:39], s94, v97
	v_cmp_lt_i32_e64 s[40:41], s94, v95
	v_cmp_ge_i32_e64 s[34:35], s94, v95
	v_cmp_lt_i32_e64 s[36:37], s94, v94
	v_cmp_ge_i32_e64 s[28:29], s94, v94
	v_cmp_lt_i32_e64 s[30:31], s94, v93
	v_cmp_ge_i32_e64 s[24:25], s94, v93
	v_cmp_lt_i32_e64 s[26:27], s94, v92
	v_cmp_ge_i32_e64 s[20:21], s94, v92
	v_cmp_lt_i32_e64 s[22:23], s94, v89
	v_cmp_ge_i32_e64 s[14:15], s94, v89
	v_cmp_lt_i32_e64 s[18:19], s94, v86
	v_cmp_ge_i32_e64 s[10:11], s94, v86
	v_cmp_lt_i32_e64 s[12:13], s94, v84
	v_cmp_ge_i32_e64 s[0:1], s94, v84
	v_cmp_lt_i32_e64 s[8:9], s94, v100
	s_andn2_b64 vcc, exec, s[56:57]
	v_add_u32_e32 v79, v67, v80
	s_cbranch_vccnz .LBB0_1940
	v_sub_u32_e32 v64, s94, v100
	v_lshlrev_b32_e32 v145, 7, v64
	v_mov_b32_e32 v146, 12
	v_mov_b32_e32 v147, v76
	v_mov_b32_e32 v64, v79
	s_branch .LBB0_1941

.LBB0_1941:
	v_mov_b32_e32 v67, v238
	v_cmp_ge_i32_e32 vcc, s94, v78
	v_add_u32_e32 v69, v76, v79
	v_add_u32_e32 v65, 0x7f, v67
	v_ashrrev_i32_e32 v65, 7, v65
	v_add_u32_e32 v65, v65, v78
	v_cmp_lt_i32_e64 s[0:1], s94, v65
	s_and_b64 s[0:1], vcc, s[0:1]
	s_andn2_b64 vcc, exec, s[0:1]
	s_cbranch_vccnz .LBB0_1943
	v_sub_u32_e32 v64, s94, v78
	v_lshlrev_b32_e32 v145, 7, v64
	v_mov_b32_e32 v146, 13
	v_mov_b32_e32 v147, v67
	v_mov_b32_e32 v64, v69
.LBB0_1943:
	v_mov_b32_e32 v68, v239
	v_cmp_ge_i32_e32 vcc, s94, v65
	v_add_u32_e32 v67, v67, v69
	v_add_u32_e32 v66, 0x7f, v68
	v_ashrrev_i32_e32 v66, 7, v66
	v_add_u32_e32 v66, v66, v65
	v_cmp_lt_i32_e64 s[0:1], s94, v66
	s_and_b64 s[0:1], vcc, s[0:1]
	s_andn2_b64 vcc, exec, s[0:1]
	s_cbranch_vccnz .LBB0_1945
	v_sub_u32_e32 v64, s94, v65
	v_lshlrev_b32_e32 v145, 7, v64
	v_mov_b32_e32 v146, 14
	v_mov_b32_e32 v147, v68
	v_mov_b32_e32 v64, v67
.LBB0_1945:
	v_mov_b32_e32 v69, v240
	v_cmp_ge_i32_e32 vcc, s94, v66
	v_add_u32_e32 v70, v68, v67
	v_add_u32_e32 v65, 0x7f, v69
	v_ashrrev_i32_e32 v65, 7, v65
	v_add_u32_e32 v65, v65, v66
	v_cmp_lt_i32_e64 s[0:1], s94, v65
	s_and_b64 s[0:1], vcc, s[0:1]
	s_andn2_b64 vcc, exec, s[0:1]
	s_cbranch_vccnz .LBB0_1947
	v_sub_u32_e32 v64, s94, v66
	v_lshlrev_b32_e32 v145, 7, v64
	v_mov_b32_e32 v146, 15
	v_mov_b32_e32 v147, v69
	v_mov_b32_e32 v64, v70
.LBB0_1947:
	v_mov_b32_e32 v68, v241
	v_cmp_ge_i32_e32 vcc, s94, v65
	v_add_u32_e32 v70, v69, v70
	v_add_u32_e32 v66, 0x7f, v68
	v_ashrrev_i32_e32 v66, 7, v66
	v_add_u32_e32 v67, v66, v65
	v_cmp_lt_i32_e64 s[0:1], s94, v67
	s_and_b64 s[0:1], vcc, s[0:1]
	s_andn2_b64 vcc, exec, s[0:1]
	s_cbranch_vccnz .LBB0_1949
	v_sub_u32_e32 v64, s94, v65
	v_lshlrev_b32_e32 v145, 7, v64
	v_mov_b32_e32 v146, 16
	v_mov_b32_e32 v147, v68
	v_mov_b32_e32 v64, v70
.LBB0_1949:
	v_mov_b32_e32 v69, v242
	v_cmp_ge_i32_e32 vcc, s94, v67
	v_add_u32_e32 v68, v68, v70
	v_add_u32_e32 v65, 0x7f, v69
	v_ashrrev_i32_e32 v65, 7, v65
	v_add_u32_e32 v66, v65, v67
	v_cmp_lt_i32_e64 s[0:1], s94, v66
	s_and_b64 s[0:1], vcc, s[0:1]
	s_andn2_b64 vcc, exec, s[0:1]
	s_cbranch_vccnz .LBB0_1951
	v_sub_u32_e32 v64, s94, v67
	v_lshlrev_b32_e32 v145, 7, v64
	v_mov_b32_e32 v146, 17
	v_mov_b32_e32 v147, v69
	v_mov_b32_e32 v64, v68
.LBB0_1951:
	v_mov_b32_e32 v67, v243
	v_cmp_ge_i32_e32 vcc, s94, v66
	v_add_u32_e32 v69, v69, v68
	v_add_u32_e32 v65, 0x7f, v67
	v_ashrrev_i32_e32 v65, 7, v65
	v_add_u32_e32 v65, v65, v66
	v_cmp_lt_i32_e64 s[0:1], s94, v65
	s_and_b64 s[0:1], vcc, s[0:1]
	s_andn2_b64 vcc, exec, s[0:1]
	s_cbranch_vccnz .LBB0_1953
	v_sub_u32_e32 v64, s94, v66
	v_lshlrev_b32_e32 v145, 7, v64
	v_mov_b32_e32 v146, 18
	v_mov_b32_e32 v147, v67
	v_mov_b32_e32 v64, v69
.LBB0_1953:
	v_mov_b32_e32 v68, v244
	v_cmp_ge_i32_e32 vcc, s94, v65
	v_add_u32_e32 v69, v67, v69
	v_add_u32_e32 v66, 0x7f, v68
	v_ashrrev_i32_e32 v66, 7, v66
	v_add_u32_e32 v66, v66, v65
	v_cmp_lt_i32_e64 s[0:1], s94, v66
	s_and_b64 s[0:1], vcc, s[0:1]
	s_andn2_b64 vcc, exec, s[0:1]
	s_cbranch_vccnz .LBB0_1955
	v_sub_u32_e32 v64, s94, v65
	v_lshlrev_b32_e32 v145, 7, v64
	v_mov_b32_e32 v146, 19
	v_mov_b32_e32 v147, v68
	v_mov_b32_e32 v64, v69
.LBB0_1955:
	v_mov_b32_e32 v67, v245
	v_cmp_ge_i32_e32 vcc, s94, v66
	v_add_u32_e32 v69, v68, v69
	v_add_u32_e32 v65, 0x7f, v67
	v_ashrrev_i32_e32 v65, 7, v65
	v_add_u32_e32 v65, v65, v66
	v_cmp_lt_i32_e64 s[0:1], s94, v65
	s_and_b64 s[0:1], vcc, s[0:1]
	s_andn2_b64 vcc, exec, s[0:1]
	s_cbranch_vccnz .LBB0_1957
	v_sub_u32_e32 v64, s94, v66
	v_lshlrev_b32_e32 v145, 7, v64
	v_mov_b32_e32 v146, 20
	v_mov_b32_e32 v147, v67
	v_mov_b32_e32 v64, v69
.LBB0_1957:
	v_mov_b32_e32 v68, v246
	v_cmp_ge_i32_e32 vcc, s94, v65
	v_add_u32_e32 v69, v67, v69
	v_add_u32_e32 v66, 0x7f, v68
	v_ashrrev_i32_e32 v66, 7, v66
	v_add_u32_e32 v66, v66, v65
	v_cmp_lt_i32_e64 s[0:1], s94, v66
	s_and_b64 s[0:1], vcc, s[0:1]
	s_andn2_b64 vcc, exec, s[0:1]
	s_cbranch_vccnz .LBB0_1959
	v_sub_u32_e32 v64, s94, v65
	v_lshlrev_b32_e32 v145, 7, v64
	v_mov_b32_e32 v146, 21
	v_mov_b32_e32 v147, v68
	v_mov_b32_e32 v64, v69
.LBB0_1959:
	v_mov_b32_e32 v65, v247
	v_cmp_ge_i32_e32 vcc, s94, v66
	v_add_u32_e32 v68, v68, v69
	v_add_u32_e32 v67, 0x7f, v65
	v_ashrrev_i32_e32 v67, 7, v67
	v_add_u32_e32 v67, v67, v66
	v_cmp_lt_i32_e64 s[0:1], s94, v67
	s_and_b64 s[0:1], vcc, s[0:1]
	s_andn2_b64 vcc, exec, s[0:1]
	s_cbranch_vccnz .LBB0_1961
	v_sub_u32_e32 v64, s94, v66
	v_lshlrev_b32_e32 v145, 7, v64
	v_mov_b32_e32 v146, 22
	v_mov_b32_e32 v147, v65
	v_mov_b32_e32 v64, v68
.LBB0_1961:
	v_mov_b32_e32 v66, v248
	v_cmp_ge_i32_e32 vcc, s94, v67
	v_add_u32_e32 v69, 0x7f, v66
	v_ashrrev_i32_e32 v69, 7, v69
	v_add_u32_e32 v69, v69, v67
	v_cmp_lt_i32_e64 s[0:1], s94, v69
	s_and_b64 s[0:1], vcc, s[0:1]
	s_andn2_b64 vcc, exec, s[0:1]
	s_cbranch_vccnz .LBB0_1963
	v_add_u32_e32 v64, v65, v68
	v_sub_u32_e32 v65, s94, v67
	v_lshlrev_b32_e32 v145, 7, v65
	v_mov_b32_e32 v146, 23
	v_mov_b32_e32 v147, v66
